# gdn_pre S2: L2 warm-up loads for the six late segment-2 rows issued with the first batch
# speedup vs baseline: 1.0063x; 1.0063x over previous
.LBB0_228:
	s_ashr_i32 s8, s72, 8
	s_mov_b32 s9, s14
	s_and_b32 s42, s72, 31
	v_mbcnt_lo_u32_b32 v152, -1, 0
	v_mbcnt_hi_u32_b32 v152, -1, v152
	s_lshl_b32 s44, s8, 11
	s_add_i32 s8, s85, 0xffffff80
	s_and_b32 s8, s8, 0x80
	v_or_b32_e32 v28, s7, v152
	s_lshl_b32 s8, s8, 2
	s_add_i32 s76, s18, s8
	v_ashrrev_i32_e32 v75, 2, v28
	s_lshl_b32 s8, s9, 7
	v_and_b32_e32 v72, -4, v75
	s_ashr_i32 s9, s8, 31
	v_lshl_add_u32 v73, s42, 6, v72
	s_add_i32 s45, s44, -3
	s_lshl_b64 s[42:43], s[8:9], 1
	v_and_b32_e32 v151, 15, v152
	s_add_u32 s42, s96, s42
	s_addc_u32 s43, s97, s43
	v_lshlrev_b32_e32 v84, 4, v151
	v_max_i32_e32 v0, 3, v73
	v_lshl_add_u64 v[58:59], s[42:43], 0, v[84:85]
	v_add_u32_e32 v60, s45, v0
	v_mad_i64_i32 v[34:35], s[42:43], v60, s82, v[58:59]
	global_load_dwordx4 v[8:11], v[34:35], off nt
	v_or_b32_e32 v74, 1, v73
	v_max_i32_e32 v0, 3, v74
	v_add_u32_e32 v62, s45, v0
	v_mad_i64_i32 v[38:39], s[42:43], v62, s82, v[58:59]
	global_load_dwordx4 v[4:7], v[38:39], off nt
	v_or_b32_e32 v76, 2, v73
	v_max_i32_e32 v0, 3, v76
	v_add_u32_e32 v66, s45, v0
	v_or_b32_e32 v0, 3, v73
	v_max_i32_e32 v0, 3, v0
	v_add_u32_e32 v77, s45, v0
	v_lshl_add_u32 v87, v72, 2, s76
	v_mov_b32_e32 v0, s76
	ds_read_b128 v[30:33], v87
	ds_read_b32 v29, v0 offset:252
	v_mad_i64_i32 v[42:43], s[42:43], v66, s82, v[58:59]
	v_mad_i64_i32 v[46:47], s[42:43], v77, s82, v[58:59]
	s_waitcnt lgkmcnt(1)
	v_mul_f32_e32 v0, 0x3fb8aa3b, v30
	s_waitcnt lgkmcnt(0)
	v_sub_f32_e32 v30, v29, v30
	v_mul_f32_e32 v30, 0x3fb8aa3b, v30
	v_exp_f32_e32 v88, v30
	v_mul_f32_e32 v30, 0x3fb8aa3b, v31
	v_exp_f32_e32 v94, v30
	v_sub_f32_e32 v30, v29, v31
	v_mul_f32_e32 v30, 0x3fb8aa3b, v30
	v_exp_f32_e32 v89, v30
	v_mul_f32_e32 v30, 0x3fb8aa3b, v32
	v_exp_f32_e32 v90, v30
	v_sub_f32_e32 v30, v29, v32
	v_sub_f32_e32 v29, v29, v33
	global_load_dwordx4 v[20:23], v[42:43], off nt
	global_load_dwordx4 v[12:15], v[46:47], off nt
	v_mul_f32_e32 v29, 0x3fb8aa3b, v29
	v_cmp_gt_i32_e32 vcc, 3, v73
	v_lshl_add_u64 v[70:71], v[58:59], 0, s[28:29]
	v_exp_f32_e32 v86, v0
	v_max_i32_e32 v0, -1, v73
	v_exp_f32_e32 v93, v29
	v_add3_u32 v78, v0, s44, 1
	v_max_i32_e32 v16, -2, v73
	v_max_i32_e32 v24, -3, v73
	global_load_dwordx4 v[38:41], v[38:39], off offset:2048 nt
	v_mad_i64_i32 v[50:51], s[42:43], v78, s82, v[58:59]
	v_add3_u32 v79, v16, s44, 2
	v_add3_u32 v80, v24, s44, 3
	global_load_dwordx4 v[0:3], v[50:51], off nt
	v_mad_i64_i32 v[54:55], s[42:43], v79, s82, v[58:59]
	v_mad_i64_i32 v[56:57], s[42:43], v80, s82, v[58:59]
	v_mul_f32_e32 v30, 0x3fb8aa3b, v30
	v_mad_i64_i32 v[58:59], s[42:43], v60, s82, v[70:71]
	v_cmp_gt_i32_e64 s[52:53], 3, v74
	global_load_dwordx4 v[24:27], v[56:57], off nt
	v_exp_f32_e32 v92, v30
	global_load_dwordx4 v[34:37], v[34:35], off offset:2048 nt
	v_mul_f32_e32 v30, 0x3fb8aa3b, v33
	global_load_dwordx4 v[58:61], v[58:59], off nt
	v_exp_f32_e32 v96, v30
	global_load_dwordx4 v[16:19], v[54:55], off nt
	global_load_dwordx4 v[30:33], v[54:55], off offset:2048 nt
	v_cmp_gt_i32_e64 s[44:45], 3, v76
	global_load_dwordx4 v[50:53], v[50:51], off offset:2048 nt
	v_cmp_gt_i32_e64 s[50:51], -3, v73
	global_load_dwordx4 v[54:57], v[56:57], off offset:2048 nt
	v_cmp_gt_i32_e64 s[48:49], -2, v73
	global_load_dwordx4 v[42:45], v[42:43], off offset:2048 nt
	v_lshlrev_b32_e32 v179, 3, v151
	global_load_dwordx4 v[46:49], v[46:47], off offset:2048 nt
	v_add_u32_e32 v74, s19, v84
	v_mad_i64_i32 v[222:223], s[42:43], v62, s82, v[70:71]
	global_load_dword v224, v[222:223], off
	v_mad_i64_i32 v[222:223], s[42:43], v78, s82, v[70:71]
	global_load_dword v225, v[222:223], off
	v_mad_i64_i32 v[222:223], s[42:43], v66, s82, v[70:71]
	global_load_dword v226, v[222:223], off
	v_mad_i64_i32 v[222:223], s[42:43], v77, s82, v[70:71]
	global_load_dword v227, v[222:223], off
	v_mad_i64_i32 v[222:223], s[42:43], v79, s82, v[70:71]
	global_load_dword v228, v[222:223], off
	v_mad_i64_i32 v[222:223], s[42:43], v80, s82, v[70:71]
	global_load_dword v229, v[222:223], off
	s_waitcnt vmcnt(14)
	v_cndmask_b32_e64 v29, v8, 0, vcc
	v_cndmask_b32_e64 v100, v9, 0, vcc
	v_mad_i64_i32 v[8:9], s[42:43], v62, s82, v[70:71]
	global_load_dwordx4 v[62:65], v[8:9], off nt
	v_cndmask_b32_e64 v101, v10, 0, vcc
	s_waitcnt vmcnt(14)
	v_cndmask_b32_e64 v108, v4, 0, s[52:53]
	v_cndmask_b32_e64 v106, v5, 0, s[52:53]
	v_mad_i64_i32 v[4:5], s[46:47], v78, s82, v[70:71]
	v_cndmask_b32_e64 v104, v6, 0, s[52:53]
	v_cndmask_b32_e64 v103, v7, 0, s[52:53]
	global_load_dwordx4 v[4:7], v[4:5], off nt
	v_mad_i64_i32 v[8:9], s[42:43], v66, s82, v[70:71]
	global_load_dwordx4 v[66:69], v[8:9], off nt
	v_mad_i64_i32 v[8:9], s[42:43], v77, s82, v[70:71]
	v_cmp_gt_i32_e64 s[42:43], 0, v73
	v_cndmask_b32_e64 v102, v11, 0, vcc
	global_load_dwordx4 v[8:11], v[8:9], off nt
	s_waitcnt vmcnt(16)
	v_cndmask_b32_e64 v105, v22, 0, s[44:45]
	s_waitcnt vmcnt(15)
	v_cndmask_b32_e64 v110, v12, 0, s[42:43]
	v_cndmask_b32_e64 v111, v13, 0, s[42:43]
	v_mad_i64_i32 v[12:13], s[46:47], v79, s82, v[70:71]
	global_load_dwordx4 v[76:79], v[12:13], off nt
	v_mad_i64_i32 v[12:13], s[46:47], v80, s82, v[70:71]
	global_load_dwordx4 v[80:83], v[12:13], off nt
	v_cmp_gt_i32_e64 s[46:47], -1, v73
	v_cndmask_b32_e64 v22, v23, 0, s[44:45]
	s_waitcnt vmcnt(16)
	v_cndmask_b32_e64 v128, v38, 0, s[52:53]
	v_cndmask_b32_e64 v126, v39, 0, s[52:53]
	v_cndmask_b32_e64 v140, v40, 0, s[52:53]
	v_cndmask_b32_e64 v193, v41, 0, s[52:53]
	v_cndmask_b32_e64 v107, v14, 0, s[42:43]
	v_cndmask_b32_e64 v23, v15, 0, s[42:43]
	s_waitcnt vmcnt(15)
	v_cndmask_b32_e64 v14, v0, 0, s[46:47]
	v_cndmask_b32_e64 v15, v1, 0, s[46:47]
	v_lshlrev_b32_e32 v0, 5, v151
	v_mov_b32_e32 v1, v85
	v_cndmask_b32_e64 v109, v20, 0, s[44:45]
	v_cndmask_b32_e64 v20, v2, 0, s[46:47]
	v_cndmask_b32_e64 v112, v3, 0, s[46:47]
	v_cndmask_b32_e64 v21, v21, 0, s[44:45]
	s_waitcnt vmcnt(14)
	v_cndmask_b32_e64 v199, v24, 0, s[50:51]
	v_cndmask_b32_e64 v200, v25, 0, s[50:51]
	s_waitcnt vmcnt(13)
	v_cndmask_b32_e64 v135, v34, 0, vcc
	v_cndmask_b32_e64 v137, v35, 0, vcc
	v_cndmask_b32_e64 v141, v36, 0, vcc
	v_cndmask_b32_e64 v198, v37, 0, vcc
	s_waitcnt vmcnt(12)
	v_cndmask_b32_e64 v153, v61, 0, vcc
	v_cndmask_b32_e64 v163, v60, 0, vcc
	v_cndmask_b32_e64 v170, v59, 0, vcc
	v_cndmask_b32_e64 v177, v58, 0, vcc
	s_mov_b64 vcc, 0x3000
	s_waitcnt vmcnt(9)
	v_cndmask_b32_e64 v132, v52, 0, s[46:47]
	v_cndmask_b32_e64 v133, v53, 0, s[46:47]
	s_waitcnt vmcnt(8)
	v_cndmask_b32_e64 v91, v54, 0, s[50:51]
	v_cndmask_b32_e64 v186, v55, 0, s[50:51]
	s_waitcnt vmcnt(7)
	v_cndmask_b32_e64 v129, v42, 0, s[44:45]
	v_cndmask_b32_e64 v127, v43, 0, s[44:45]
	v_cndmask_b32_e64 v139, v44, 0, s[44:45]
	v_cndmask_b32_e64 v192, v45, 0, s[44:45]
	v_cndmask_b32_e64 v187, v56, 0, s[50:51]
	v_cndmask_b32_e64 v188, v57, 0, s[50:51]
	v_cndmask_b32_e64 v201, v26, 0, s[50:51]
	v_cndmask_b32_e64 v202, v27, 0, s[50:51]
	v_cndmask_b32_e64 v142, v32, 0, s[48:49]
	v_cndmask_b32_e64 v143, v33, 0, s[48:49]
	s_waitcnt vmcnt(5)
	v_cndmask_b32_e64 v154, v65, 0, s[52:53]
	v_cndmask_b32_e64 v164, v64, 0, s[52:53]
	v_cndmask_b32_e64 v171, v63, 0, s[52:53]
	v_cndmask_b32_e64 v178, v62, 0, s[52:53]
	s_lshl_b64 s[52:53], s[8:9], 2
	s_add_u32 s52, s80, s52
	s_addc_u32 s53, s81, s53
	v_lshl_add_u64 v[2:3], s[52:53], 0, v[0:1]
	global_load_dwordx4 v[52:55], v0, s[52:53] offset:16
	global_load_dwordx4 v[24:27], v0, s[52:53]
	v_lshl_add_u64 v[12:13], v[2:3], 0, vcc
	s_mov_b64 vcc, 0x6000
	s_waitcnt vmcnt(5)
	v_cndmask_b32_e64 v155, v69, 0, s[44:45]
	v_cndmask_b32_e64 v165, v68, 0, s[44:45]
	global_load_dwordx4 v[56:59], v[12:13], off offset:16
	v_cndmask_b32_e64 v172, v67, 0, s[44:45]
	v_lshl_add_u64 v[12:13], v[2:3], 0, vcc
	v_cndmask_b32_e64 v180, v66, 0, s[44:45]
	s_mov_b64 s[44:45], 0x9000
	global_load_dwordx4 v[60:63], v[12:13], off offset:16
	v_lshl_add_u64 v[12:13], v[2:3], 0, s[44:45]
	global_load_dwordx4 v[64:67], v[12:13], off offset:16
	s_movk_i32 s9, 0x3000
	v_add_co_u32_e32 v0, vcc, s9, v2
	s_movk_i32 s9, 0x6000
	s_nop 0
	v_addc_co_u32_e32 v1, vcc, 0, v3, vcc
	global_load_dwordx4 v[32:35], v[0:1], off
	v_add_co_u32_e32 v0, vcc, s9, v2
	s_mov_b32 s9, 0x9000
	s_nop 0
	v_addc_co_u32_e32 v1, vcc, 0, v3, vcc
	global_load_dwordx4 v[40:43], v[0:1], off
	v_add_co_u32_e32 v0, vcc, s9, v2
	v_cndmask_b32_e64 v138, v48, 0, s[42:43]
	s_nop 0
	v_addc_co_u32_e32 v1, vcc, 0, v3, vcc
	v_cndmask_b32_e64 v191, v49, 0, s[42:43]
	v_cndmask_b32_e64 v131, v50, 0, s[46:47]
	v_cndmask_b32_e64 v130, v51, 0, s[46:47]
	global_load_dwordx4 v[48:51], v[0:1], off
	v_cndmask_b32_e64 v203, v16, 0, s[48:49]
	v_cndmask_b32_e64 v204, v17, 0, s[48:49]
	v_lshlrev_b32_e32 v16, 16, v101
	v_and_b32_e32 v17, 0xffff0000, v101
	v_cndmask_b32_e64 v205, v18, 0, s[48:49]
	v_cndmask_b32_e64 v206, v19, 0, s[48:49]
	s_waitcnt vmcnt(9)
	v_cndmask_b32_e64 v175, v77, 0, s[48:49]
	v_cndmask_b32_e64 v184, v76, 0, s[48:49]
	v_lshlrev_b32_e32 v2, 16, v102
	v_and_b32_e32 v3, 0xffff0000, v102
	v_lshlrev_b32_e32 v18, 16, v103
	v_and_b32_e32 v19, 0xffff0000, v103
	v_lshlrev_b32_e32 v102, 16, v22
	v_and_b32_e32 v103, 0xffff0000, v22
	v_lshlrev_b32_e32 v76, 16, v23
	v_and_b32_e32 v77, 0xffff0000, v23
	v_lshlrev_b32_e32 v22, 16, v104
	v_and_b32_e32 v23, 0xffff0000, v104
	v_lshlrev_b32_e32 v104, 16, v105
	v_and_b32_e32 v105, 0xffff0000, v105
	v_cndmask_b32_e64 v158, v79, 0, s[48:49]
	v_cndmask_b32_e64 v168, v78, 0, s[48:49]
	v_lshlrev_b32_e32 v78, 16, v107
	v_and_b32_e32 v79, 0xffff0000, v107
	v_cndmask_b32_e64 v189, v30, 0, s[48:49]
	v_cndmask_b32_e64 v190, v31, 0, s[48:49]
	v_cmp_lt_i32_e32 vcc, v95, v160
	v_and_b32_e32 v107, 0xffff0000, v21
	s_waitcnt vmcnt(8)
	v_cndmask_b32_e64 v176, v81, 0, s[50:51]
	v_cndmask_b32_e32 v0, v159, v95, vcc
	v_cmp_lt_i32_e32 vcc, v144, v160
	v_cndmask_b32_e64 v182, v80, 0, s[50:51]
	v_lshlrev_b32_e32 v195, 2, v0
	v_cndmask_b32_e32 v0, v159, v144, vcc
	v_cmp_lt_i32_e32 vcc, v145, v160
	v_lshlrev_b32_e32 v80, 16, v111
	v_and_b32_e32 v81, 0xffff0000, v111
	v_lshlrev_b32_e32 v196, 2, v0
	v_cndmask_b32_e32 v0, v159, v145, vcc
	v_cmp_lt_i32_e32 vcc, v146, v160
	v_lshlrev_b32_e32 v197, 2, v0
	v_cndmask_b32_e64 v134, v46, 0, s[42:43]
	v_cndmask_b32_e32 v0, v159, v146, vcc
	v_lshlrev_b32_e32 v161, 2, v0
	s_waitcnt vmcnt(7)
	v_pk_fma_f32 v[16:17], v[52:53], v[16:17], 0 op_sel_hi:[1,1,0]
	v_ashrrev_i32_e32 v0, 5, v28
	v_cndmask_b32_e64 v136, v47, 0, s[42:43]
	v_lshlrev_b32_e32 v46, 16, v108
	v_and_b32_e32 v47, 0xffff0000, v108
	v_pk_fma_f32 v[2:3], v[54:55], v[2:3], 0 op_sel_hi:[1,1,0]
	s_waitcnt vmcnt(5)
	v_pk_fma_f32 v[16:17], v[56:57], v[22:23], v[16:17]
	v_lshlrev_b32_e32 v108, 16, v109
	v_and_b32_e32 v109, 0xffff0000, v109
	v_cndmask_b32_e64 v162, v83, 0, s[50:51]
	v_cndmask_b32_e64 v169, v82, 0, s[50:51]
	s_waitcnt vmcnt(4)
	v_pk_fma_f32 v[16:17], v[60:61], v[104:105], v[16:17]
	v_pk_fma_f32 v[2:3], v[58:59], v[18:19], v[2:3]
	s_waitcnt vmcnt(3)
	v_pk_fma_f32 v[30:31], v[64:65], v[78:79], v[16:17]
	v_lshlrev_b32_e32 v82, 16, v110
	v_mul_f32_e32 v16, 0xbfb8aa3b, v30
	v_exp_f32_e32 v16, v16
	v_mul_f32_e32 v17, 0xbfb8aa3b, v31
	v_exp_f32_e32 v17, v17
	v_and_b32_e32 v83, 0xffff0000, v110
	v_add_f32_e32 v16, 1.0, v16
	v_rcp_f32_e32 v36, v16
	v_add_f32_e32 v16, 1.0, v17
	v_rcp_f32_e32 v37, v16
	v_pk_fma_f32 v[18:19], v[54:55], v[18:19], 0 op_sel_hi:[1,1,0]
	v_or_b32_e32 v68, s8, v179
	v_pk_fma_f32 v[18:19], v[58:59], v[102:103], v[18:19]
	v_pk_mul_f32 v[118:119], v[30:31], v[36:37]
	v_lshlrev_b32_e32 v30, 16, v100
	v_and_b32_e32 v31, 0xffff0000, v100
	v_pk_fma_f32 v[30:31], v[26:27], v[30:31], 0 op_sel_hi:[1,1,0]
	v_lshlrev_b32_e32 v36, 16, v106
	v_and_b32_e32 v37, 0xffff0000, v106
	s_waitcnt vmcnt(2)
	v_pk_fma_f32 v[30:31], v[34:35], v[36:37], v[30:31]
	v_lshlrev_b32_e32 v106, 16, v21
	s_waitcnt vmcnt(1)
	v_pk_fma_f32 v[30:31], v[42:43], v[106:107], v[30:31]
	v_ashrrev_i32_e32 v69, 31, v68
	s_waitcnt vmcnt(0)
	v_pk_fma_f32 v[30:31], v[50:51], v[80:81], v[30:31]
	v_lshlrev_b32_e32 v116, 16, v112
	v_mul_f32_e32 v21, 0xbfb8aa3b, v30
	v_exp_f32_e32 v21, v21
	v_mul_f32_e32 v28, 0xbfb8aa3b, v31
	v_exp_f32_e32 v28, v28
	v_and_b32_e32 v117, 0xffff0000, v112
	v_add_f32_e32 v21, 1.0, v21
	v_rcp_f32_e32 v44, v21
	v_add_f32_e32 v21, 1.0, v28
	v_lshlrev_b32_e32 v28, 16, v29
	v_and_b32_e32 v29, 0xffff0000, v29
	v_pk_fma_f32 v[28:29], v[24:25], v[28:29], 0 op_sel_hi:[1,1,0]
	v_rcp_f32_e32 v45, v21
	v_pk_fma_f32 v[28:29], v[32:33], v[46:47], v[28:29]
	v_pk_fma_f32 v[18:19], v[62:63], v[76:77], v[18:19]
	v_pk_fma_f32 v[28:29], v[40:41], v[108:109], v[28:29]
	v_cndmask_b32_e64 v173, v9, 0, s[42:43]
	v_pk_fma_f32 v[28:29], v[48:49], v[82:83], v[28:29]
	v_cndmask_b32_e64 v181, v8, 0, s[42:43]
	v_mul_f32_e32 v21, 0xbfb8aa3b, v28
	v_lshl_add_u64 v[8:9], v[68:69], 2, s[80:81]
	v_exp_f32_e32 v21, v21
	v_mul_f32_e32 v69, 0xbfb8aa3b, v29
	v_pk_fma_f32 v[18:19], v[66:67], v[116:117], v[18:19]
	v_exp_f32_e32 v69, v69
	v_pk_mul_f32 v[120:121], v[30:31], v[44:45]
	v_mul_f32_e32 v31, 0xbfb8aa3b, v18
	v_exp_f32_e32 v44, v31
	v_mul_f32_e32 v31, 0xbfb8aa3b, v19
	v_exp_f32_e32 v45, v31
	v_add_f32_e32 v21, 1.0, v21
	v_rcp_f32_e32 v30, v21
	v_add_f32_e32 v21, 1.0, v69
	v_rcp_f32_e32 v31, v21
	v_add_f32_e32 v21, 1.0, v44
	v_rcp_f32_e32 v44, v21
	v_add_f32_e32 v21, 1.0, v45
	v_rcp_f32_e32 v45, v21
	v_lshlrev_b32_e32 v114, 16, v20
	v_and_b32_e32 v115, 0xffff0000, v20
	v_pk_mul_f32 v[208:209], v[28:29], v[30:31]
	v_pk_mul_f32 v[122:123], v[18:19], v[44:45]
	v_pk_fma_f32 v[18:19], v[52:53], v[22:23], 0 op_sel_hi:[1,1,0]
	v_pk_fma_f32 v[30:31], v[26:27], v[36:37], 0 op_sel_hi:[1,1,0]
	v_pk_fma_f32 v[18:19], v[56:57], v[104:105], v[18:19]
	v_pk_fma_f32 v[30:31], v[34:35], v[106:107], v[30:31]
	v_pk_fma_f32 v[18:19], v[60:61], v[78:79], v[18:19]
	v_lshlrev_b32_e32 v112, 16, v15
	v_pk_fma_f32 v[18:19], v[64:65], v[114:115], v[18:19]
	v_and_b32_e32 v113, 0xffff0000, v15
	v_mul_f32_e32 v20, 0xbfb8aa3b, v18
	v_exp_f32_e32 v22, v20
	v_mul_f32_e32 v20, 0xbfb8aa3b, v19
	v_exp_f32_e32 v23, v20
	v_pk_fma_f32 v[30:31], v[42:43], v[80:81], v[30:31]
	v_add_f32_e32 v22, 1.0, v22
	v_pk_fma_f32 v[30:31], v[50:51], v[112:113], v[30:31]
	v_add_f32_e32 v23, 1.0, v23
	v_mul_f32_e32 v15, 0xbfb8aa3b, v30
	v_exp_f32_e32 v15, v15
	v_rcp_f32_e32 v22, v22
	v_rcp_f32_e32 v23, v23
	v_lshlrev_b32_e32 v110, 16, v14
	v_add_f32_e32 v15, 1.0, v15
	v_and_b32_e32 v111, 0xffff0000, v14
	v_pk_mul_f32 v[124:125], v[18:19], v[22:23]
	v_rcp_f32_e32 v18, v15
	v_pk_fma_f32 v[14:15], v[24:25], v[46:47], 0 op_sel_hi:[1,1,0]
	v_mul_f32_e32 v36, 0xbfb8aa3b, v31
	v_pk_fma_f32 v[14:15], v[32:33], v[108:109], v[14:15]
	v_pk_fma_f32 v[2:3], v[62:63], v[102:103], v[2:3]
	v_pk_fma_f32 v[14:15], v[40:41], v[82:83], v[14:15]
	v_exp_f32_e32 v36, v36
	v_pk_fma_f32 v[14:15], v[48:49], v[110:111], v[14:15]
	v_cndmask_b32_e64 v156, v11, 0, s[42:43]
	v_mul_f32_e32 v22, 0xbfb8aa3b, v14
	v_mul_f32_e32 v23, 0xbfb8aa3b, v15
	v_exp_f32_e32 v22, v22
	v_exp_f32_e32 v23, v23
	v_cndmask_b32_e64 v166, v10, 0, s[42:43]
	v_pk_fma_f32 v[10:11], v[66:67], v[76:77], v[2:3]
	v_add_f32_e32 v22, 1.0, v22
	v_mul_f32_e32 v2, 0xbfb8aa3b, v10
	v_exp_f32_e32 v12, v2
	v_mul_f32_e32 v2, 0xbfb8aa3b, v11
	v_add_f32_e32 v23, 1.0, v23
	v_exp_f32_e32 v13, v2
	v_add_f32_e32 v19, 1.0, v36
	v_rcp_f32_e32 v22, v22
	v_rcp_f32_e32 v23, v23
	v_rcp_f32_e32 v19, v19
	v_add_f32_e32 v12, 1.0, v12
	v_add_f32_e32 v13, 1.0, v13
	v_pk_mul_f32 v[212:213], v[14:15], v[22:23]
	v_rcp_f32_e32 v12, v12
	v_rcp_f32_e32 v13, v13
	v_pk_mul_f32 v[28:29], v[208:209], v[208:209]
	v_pk_mul_f32 v[210:211], v[30:31], v[18:19]
	v_pk_mul_f32 v[14:15], v[212:213], v[212:213]
	v_pk_mul_f32 v[100:101], v[120:121], v[120:121]
	v_pk_mul_f32 v[18:19], v[210:211], v[210:211]
	v_mov_b32_e32 v22, v14
	v_mov_b32_e32 v23, v28
	v_mov_b32_e32 v28, v15
	v_pk_add_f32 v[14:15], v[22:23], v[28:29]
	v_mov_b32_e32 v22, v18
	v_mov_b32_e32 v23, v100
	v_pk_mul_f32 v[38:39], v[118:119], v[118:119]
	v_pk_mul_f32 v[36:37], v[124:125], v[124:125]
	v_pk_add_f32 v[14:15], v[22:23], v[14:15]
	v_mov_b32_e32 v100, v19
	v_pk_mul_f32 v[10:11], v[10:11], v[12:13]
	v_pk_add_f32 v[14:15], v[100:101], v[14:15]
	v_mov_b32_e32 v18, v36
	v_mov_b32_e32 v19, v38
	v_pk_mul_f32 v[12:13], v[10:11], v[10:11]
	v_pk_mul_f32 v[20:21], v[122:123], v[122:123]
	v_pk_add_f32 v[14:15], v[18:19], v[14:15]
	v_mov_b32_e32 v38, v37
	v_pk_add_f32 v[14:15], v[38:39], v[14:15]
	v_mov_b32_e32 v18, v20
	v_mov_b32_e32 v19, v12
	v_pk_add_f32 v[14:15], v[18:19], v[14:15]
	v_mov_b32_e32 v12, v21
	v_pk_add_f32 v[18:19], v[12:13], v[14:15]
	ds_bpermute_b32 v21, v195, v19
	ds_bpermute_b32 v20, v195, v18
	v_bitop3_b32 v0, v0, v152, 7 bitop3:0x78
	v_lshlrev_b32_e32 v1, 1, v75
	v_lshlrev_b32_e32 v0, 4, v0
	v_and_b32_e32 v1, 8, v1
	s_waitcnt lgkmcnt(0)
	v_pk_add_f32 v[20:21], v[18:19], v[20:21]
	v_add3_u32 v185, s19, v0, v1
	v_add_co_u32_e32 v0, vcc, s15, v8
	ds_bpermute_b32 v45, v196, v21
	ds_bpermute_b32 v44, v196, v20
	v_addc_co_u32_e32 v1, vcc, 0, v9, vcc
	v_add_co_u32_e32 v12, vcc, s83, v8
	v_cndmask_b32_e64 v174, v5, 0, s[46:47]
	v_cndmask_b32_e64 v183, v4, 0, s[46:47]
	v_lshl_add_u64 v[4:5], v[8:9], 0, s[28:29]
	v_lshl_add_u64 v[16:17], v[8:9], 0, s[36:37]
	v_addc_co_u32_e32 v13, vcc, 0, v9, vcc
	v_cndmask_b32_e64 v157, v7, 0, s[46:47]
	v_cndmask_b32_e64 v167, v6, 0, s[46:47]
	global_load_dwordx4 v[0:3], v[0:1], off
	s_nop 0
	global_load_dwordx4 v[4:7], v[4:5], off offset:16
	s_nop 0
	global_load_dwordx4 v[12:15], v[12:13], off
	s_nop 0
	global_load_dwordx4 v[28:31], v[16:17], off offset:16
	v_add_co_u32_e32 v16, vcc, s95, v8
	v_lshl_add_u64 v[22:23], v[8:9], 0, s[38:39]
	s_nop 0
	v_addc_co_u32_e32 v17, vcc, 0, v9, vcc
	s_waitcnt lgkmcnt(0)
	v_pk_add_f32 v[20:21], v[20:21], v[44:45]
	global_load_dwordx4 v[16:19], v[16:17], off
	s_nop 0
	global_load_dwordx4 v[36:39], v[22:23], off offset:16
	ds_bpermute_b32 v23, v197, v21
	ds_bpermute_b32 v22, v197, v20
	v_lshl_add_u64 v[46:47], v[8:9], 0, s[40:41]
	v_add_co_u32_e32 v8, vcc, s33, v8
	s_ashr_i32 s73, s72, 31
	s_waitcnt lgkmcnt(0)
	v_pk_add_f32 v[214:215], v[20:21], v[22:23]
	ds_bpermute_b32 v217, v161, v215
	ds_bpermute_b32 v216, v161, v214
	v_addc_co_u32_e32 v9, vcc, 0, v9, vcc
	global_load_dwordx4 v[20:23], v[8:9], off
	s_nop 0
	global_load_dwordx4 v[44:47], v[46:47], off offset:16
	s_lshl_b64 s[48:49], s[72:73], 14
	s_waitcnt lgkmcnt(0)
	v_pk_add_f32 v[8:9], v[214:215], v[216:217]
	s_add_u32 s8, s20, s48
	v_pk_add_f32 v[214:215], v[8:9], s[6:7] op_sel_hi:[1,0]
	s_addc_u32 s9, s21, s49
	v_mul_f32_e32 v8, 0x4b800000, v215
	v_cmp_gt_f32_e32 vcc, s12, v215
	v_mul_f32_e32 v69, 0x4b800000, v214
	v_ashrrev_i32_e32 v73, 31, v72
	v_cndmask_b32_e32 v8, v215, v8, vcc
	v_rsq_f32_e32 v8, v8
	v_lshl_add_u64 v[98:99], v[72:73], 1, s[8:9]
	s_add_u32 s8, s16, s48
	s_addc_u32 s9, s17, s49
	v_mul_f32_e32 v9, 0x45800000, v8
	v_cndmask_b32_e32 v8, v8, v9, vcc
	v_cmp_gt_f32_e32 vcc, s12, v214
	v_mul_f32_e32 v8, 0x3db504f3, v8
	v_pk_mul_f32 v[208:209], v[208:209], v[8:9] op_sel_hi:[1,0]
	v_cndmask_b32_e32 v69, v214, v69, vcc
	v_rsq_f32_e32 v69, v69
	v_pk_mul_f32 v[120:121], v[120:121], v[8:9] op_sel_hi:[1,0]
	v_lshl_add_u64 v[70:71], s[8:9], 0, v[84:85]
	v_mad_u64_u32 v[100:101], s[8:9], v72, s54, v[74:75]
	v_lshlrev_b32_e32 v72, 7, v72
	v_pk_mul_f32 v[218:219], v[118:119], v[8:9] op_sel_hi:[1,0]
	v_pk_mul_f32 v[220:221], v[10:11], v[8:9] op_sel_hi:[1,0]
	v_cvt_pk_bf16_f32 v9, v120, v121
	v_pk_mul_f32 v[118:119], v[86:87], v[208:209] op_sel_hi:[0,1]
	v_pk_mul_f32 v[120:121], v[86:87], v[120:121] op_sel_hi:[0,1]
	v_pk_fma_f32 v[102:103], v[54:55], v[102:103], 0 op_sel_hi:[1,1,0]
	v_ashrrev_i32_e32 v73, 31, v72
	v_cvt_pk_bf16_f32 v8, v208, v209
	v_cvt_pk_bf16_f32 v118, v118, v119
	v_cvt_pk_bf16_f32 v119, v120, v121
	v_pk_mul_f32 v[120:121], v[86:87], v[218:219] op_sel_hi:[0,1]
	v_pk_mul_f32 v[208:209], v[86:87], v[220:221] op_sel_hi:[0,1]
	v_pk_fma_f32 v[102:103], v[58:59], v[76:77], v[102:103]
	v_lshl_add_u64 v[216:217], v[72:73], 1, v[70:71]
	v_cvt_pk_bf16_f32 v120, v120, v121
	v_cvt_pk_bf16_f32 v121, v208, v209
	v_mul_f32_e32 v73, 0x45800000, v69
	v_lshlrev_b32_e32 v208, 16, v206
	v_and_b32_e32 v209, 0xffff0000, v206
	v_pk_fma_f32 v[102:103], v[62:63], v[116:117], v[102:103]
	v_cndmask_b32_e32 v69, v69, v73, vcc
	v_pk_fma_f32 v[102:103], v[66:67], v[208:209], v[102:103]
	v_mul_f32_e32 v84, 0x3db504f3, v69
	v_mul_f32_e32 v69, 0xbfb8aa3b, v102
	v_exp_f32_e32 v69, v69
	v_mul_f32_e32 v73, 0xbfb8aa3b, v103
	v_exp_f32_e32 v73, v73
	v_pk_fma_f32 v[104:105], v[52:53], v[104:105], 0 op_sel_hi:[1,1,0]
	global_store_dwordx4 v[216:217], v[118:121], off
	v_pk_fma_f32 v[104:105], v[56:57], v[78:79], v[104:105]
	v_add_f32_e32 v69, 1.0, v69
	v_pk_mul_f32 v[118:119], v[210:211], v[84:85] op_sel_hi:[1,0]
	v_lshlrev_b32_e32 v210, 16, v205
	v_and_b32_e32 v211, 0xffff0000, v205
	v_pk_fma_f32 v[104:105], v[60:61], v[114:115], v[104:105]
	v_rcp_f32_e32 v206, v69
	v_pk_fma_f32 v[104:105], v[64:65], v[210:211], v[104:105]
	v_add_f32_e32 v69, 1.0, v73
	v_mul_f32_e32 v73, 0xbfb8aa3b, v104
	v_exp_f32_e32 v73, v73
	v_mul_f32_e32 v101, 0xbfb8aa3b, v105
	v_exp_f32_e32 v101, v101
	v_rcp_f32_e32 v207, v69
	v_add_f32_e32 v69, 1.0, v73
	v_pk_mul_f32 v[120:121], v[212:213], v[84:85] op_sel_hi:[1,0]
	v_rcp_f32_e32 v212, v69
	v_add_f32_e32 v69, 1.0, v101
	v_rcp_f32_e32 v213, v69
	v_pk_fma_f32 v[106:107], v[26:27], v[106:107], 0 op_sel_hi:[1,1,0]
	v_pk_fma_f32 v[108:109], v[24:25], v[108:109], 0 op_sel_hi:[1,1,0]
	v_pk_fma_f32 v[106:107], v[34:35], v[80:81], v[106:107]
	v_pk_mul_f32 v[104:105], v[104:105], v[212:213]
	v_lshlrev_b32_e32 v212, 16, v204
	v_and_b32_e32 v213, 0xffff0000, v204
	v_pk_fma_f32 v[106:107], v[42:43], v[112:113], v[106:107]
	v_pk_fma_f32 v[108:109], v[32:33], v[82:83], v[108:109]
	v_pk_fma_f32 v[106:107], v[50:51], v[212:213], v[106:107]
	v_pk_fma_f32 v[54:55], v[54:55], v[76:77], 0 op_sel_hi:[1,1,0]
	v_mul_f32_e32 v69, 0xbfb8aa3b, v106
	v_exp_f32_e32 v69, v69
	v_mul_f32_e32 v73, 0xbfb8aa3b, v107
	v_exp_f32_e32 v73, v73
	v_lshlrev_b32_e32 v216, 16, v203
	v_add_f32_e32 v69, 1.0, v69
	v_and_b32_e32 v217, 0xffff0000, v203
	v_pk_fma_f32 v[108:109], v[40:41], v[110:111], v[108:109]
	v_pk_fma_f32 v[54:55], v[58:59], v[116:117], v[54:55]
	v_cvt_pk_bf16_f32 v10, v218, v219
	v_rcp_f32_e32 v214, v69
	v_add_f32_e32 v69, 1.0, v73
	v_pk_fma_f32 v[108:109], v[48:49], v[216:217], v[108:109]
	v_lshlrev_b32_e32 v218, 16, v202
	v_and_b32_e32 v219, 0xffff0000, v202
	v_pk_fma_f32 v[54:55], v[62:63], v[208:209], v[54:55]
	v_rcp_f32_e32 v215, v69
	v_mul_f32_e32 v69, 0xbfb8aa3b, v108
	v_pk_fma_f32 v[54:55], v[66:67], v[218:219], v[54:55]
	v_exp_f32_e32 v69, v69
	v_mul_f32_e32 v73, 0xbfb8aa3b, v109
	v_mul_f32_e32 v58, 0xbfb8aa3b, v54
	v_mul_f32_e32 v59, 0xbfb8aa3b, v55
	v_exp_f32_e32 v73, v73
	v_exp_f32_e32 v58, v58
	v_exp_f32_e32 v59, v59
	v_add_f32_e32 v69, 1.0, v69
	v_pk_mul_f32 v[106:107], v[106:107], v[214:215]
	v_rcp_f32_e32 v214, v69
	v_add_f32_e32 v69, 1.0, v73
	v_add_f32_e32 v58, 1.0, v58
	v_add_f32_e32 v59, 1.0, v59
	v_rcp_f32_e32 v215, v69
	v_rcp_f32_e32 v58, v58
	v_rcp_f32_e32 v59, v59
	v_pk_fma_f32 v[26:27], v[26:27], v[80:81], 0 op_sel_hi:[1,1,0]
	v_pk_fma_f32 v[24:25], v[24:25], v[82:83], 0 op_sel_hi:[1,1,0]
	v_pk_fma_f32 v[26:27], v[34:35], v[112:113], v[26:27]
	v_pk_mul_f32 v[66:67], v[108:109], v[214:215]
	v_pk_mul_f32 v[108:109], v[54:55], v[58:59]
	v_lshlrev_b32_e32 v58, 16, v200
	v_and_b32_e32 v59, 0xffff0000, v200
	v_pk_fma_f32 v[26:27], v[42:43], v[212:213], v[26:27]
	v_pk_fma_f32 v[24:25], v[32:33], v[110:111], v[24:25]
	v_pk_fma_f32 v[52:53], v[52:53], v[78:79], 0 op_sel_hi:[1,1,0]
	v_pk_fma_f32 v[26:27], v[50:51], v[58:59], v[26:27]
	v_lshlrev_b32_e32 v50, 16, v199
	v_and_b32_e32 v51, 0xffff0000, v199
	v_pk_fma_f32 v[24:25], v[40:41], v[216:217], v[24:25]
	v_pk_fma_f32 v[52:53], v[56:57], v[114:115], v[52:53]
	v_pk_fma_f32 v[24:25], v[48:49], v[50:51], v[24:25]
	v_lshlrev_b32_e32 v54, 16, v201
	v_and_b32_e32 v55, 0xffff0000, v201
	v_pk_fma_f32 v[52:53], v[60:61], v[210:211], v[52:53]
	v_mul_f32_e32 v34, 0xbfb8aa3b, v26
	v_mul_f32_e32 v32, 0xbfb8aa3b, v24
	v_mul_f32_e32 v33, 0xbfb8aa3b, v25
	v_pk_fma_f32 v[52:53], v[64:65], v[54:55], v[52:53]
	v_exp_f32_e32 v42, v34
	v_mul_f32_e32 v34, 0xbfb8aa3b, v27
	v_exp_f32_e32 v32, v32
	v_exp_f32_e32 v33, v33
	v_mul_f32_e32 v54, 0xbfb8aa3b, v52
	v_exp_f32_e32 v43, v34
	v_exp_f32_e32 v56, v54
	v_mul_f32_e32 v54, 0xbfb8aa3b, v53
	v_exp_f32_e32 v57, v54
	v_add_f32_e32 v32, 1.0, v32
	v_add_f32_e32 v33, 1.0, v33
	v_add_f32_e32 v42, 1.0, v42
	v_add_f32_e32 v43, 1.0, v43
	v_rcp_f32_e32 v32, v32
	v_rcp_f32_e32 v33, v33
	v_rcp_f32_e32 v42, v42
	v_rcp_f32_e32 v43, v43
	v_add_f32_e32 v56, 1.0, v56
	v_add_f32_e32 v57, 1.0, v57
	v_rcp_f32_e32 v56, v56
	v_rcp_f32_e32 v57, v57
	v_pk_mul_f32 v[32:33], v[24:25], v[32:33]
	v_pk_mul_f32 v[76:77], v[66:67], v[66:67]
	v_pk_mul_f32 v[42:43], v[26:27], v[42:43]
	v_pk_mul_f32 v[24:25], v[32:33], v[32:33]
	v_pk_mul_f32 v[62:63], v[106:107], v[106:107]
	v_pk_mul_f32 v[26:27], v[42:43], v[42:43]
	v_mov_b32_e32 v48, v24
	v_mov_b32_e32 v49, v76
	v_mov_b32_e32 v76, v25
	v_pk_mul_f32 v[34:35], v[52:53], v[56:57]
	v_pk_add_f32 v[24:25], v[48:49], v[76:77]
	v_mov_b32_e32 v48, v26
	v_mov_b32_e32 v49, v62
	v_pk_mul_f32 v[204:205], v[104:105], v[104:105]
	v_pk_mul_f32 v[40:41], v[34:35], v[34:35]
	v_pk_add_f32 v[24:25], v[48:49], v[24:25]
	v_mov_b32_e32 v62, v27
	v_pk_mul_f32 v[102:103], v[102:103], v[206:207]
	v_pk_add_f32 v[24:25], v[62:63], v[24:25]
	v_mov_b32_e32 v26, v40
	v_mov_b32_e32 v27, v204
	v_pk_mul_f32 v[206:207], v[102:103], v[102:103]
	v_pk_mul_f32 v[54:55], v[108:109], v[108:109]
	v_pk_add_f32 v[24:25], v[26:27], v[24:25]
	v_mov_b32_e32 v204, v41
	v_pk_add_f32 v[24:25], v[204:205], v[24:25]
	v_mov_b32_e32 v26, v54
	v_mov_b32_e32 v27, v206
	v_pk_add_f32 v[24:25], v[26:27], v[24:25]
	v_mov_b32_e32 v206, v55
	v_pk_add_f32 v[24:25], v[206:207], v[24:25]
	ds_bpermute_b32 v27, v195, v25
	ds_bpermute_b32 v26, v195, v24
	v_pk_mul_f32 v[48:49], v[94:95], v[118:119] op_sel_hi:[0,1]
	v_pk_mul_f32 v[124:125], v[124:125], v[84:85] op_sel_hi:[1,0]
	v_pk_mul_f32 v[122:123], v[122:123], v[84:85] op_sel_hi:[1,0]
	v_lshlrev_b32_e32 v80, 16, v192
	s_waitcnt lgkmcnt(0)
	v_pk_add_f32 v[26:27], v[24:25], v[26:27]
	ds_bpermute_b32 v41, v196, v27
	ds_bpermute_b32 v40, v196, v26
	v_pk_mul_f32 v[24:25], v[94:95], v[120:121] op_sel_hi:[0,1]
	v_cvt_pk_bf16_f32 v24, v24, v25
	v_cvt_pk_bf16_f32 v25, v48, v49
	v_pk_mul_f32 v[50:51], v[94:95], v[122:123] op_sel_hi:[0,1]
	s_waitcnt lgkmcnt(0)
	v_pk_add_f32 v[40:41], v[26:27], v[40:41]
	ds_bpermute_b32 v49, v197, v41
	ds_bpermute_b32 v48, v197, v40
	v_pk_mul_f32 v[26:27], v[94:95], v[124:125] op_sel_hi:[0,1]
	v_cvt_pk_bf16_f32 v26, v26, v27
	v_cvt_pk_bf16_f32 v27, v50, v51
	v_or_b32_e32 v50, 0x80, v72
	s_waitcnt lgkmcnt(0)
	v_pk_add_f32 v[40:41], v[40:41], v[48:49]
	ds_bpermute_b32 v49, v161, v41
	ds_bpermute_b32 v48, v161, v40
	v_ashrrev_i32_e32 v51, 31, v50
	v_lshl_add_u64 v[50:51], v[50:51], 1, v[70:71]
	global_store_dwordx4 v[50:51], v[24:27], off
	v_and_b32_e32 v81, 0xffff0000, v192
	v_cvt_pk_bf16_f32 v54, v124, v125
	s_waitcnt lgkmcnt(0)
	v_pk_add_f32 v[24:25], v[40:41], v[48:49]
	v_lshlrev_b32_e32 v124, 16, v139
	v_pk_add_f32 v[40:41], v[24:25], s[6:7] op_sel_hi:[1,0]
	v_and_b32_e32 v125, 0xffff0000, v139
	v_mul_f32_e32 v24, 0x4b800000, v41
	v_cmp_gt_f32_e32 vcc, s12, v41
	v_lshlrev_b32_e32 v112, 16, v136
	v_and_b32_e32 v113, 0xffff0000, v136
	v_cndmask_b32_e32 v24, v41, v24, vcc
	v_rsq_f32_e32 v26, v24
	v_or_b32_e32 v24, 0x100, v72
	v_ashrrev_i32_e32 v25, 31, v24
	v_lshl_add_u64 v[48:49], v[24:25], 1, v[70:71]
	v_mul_f32_e32 v24, 0x45800000, v26
	v_cndmask_b32_e32 v24, v26, v24, vcc
	v_mul_f32_e32 v24, 0x3db504f3, v24
	v_pk_mul_f32 v[26:27], v[66:67], v[24:25] op_sel_hi:[1,0]
	v_pk_mul_f32 v[50:51], v[106:107], v[24:25] op_sel_hi:[1,0]
	v_pk_mul_f32 v[60:61], v[104:105], v[24:25] op_sel_hi:[1,0]
	v_pk_mul_f32 v[62:63], v[102:103], v[24:25] op_sel_hi:[1,0]
	v_cvt_pk_bf16_f32 v56, v26, v27
	v_pk_mul_f32 v[24:25], v[90:91], v[26:27] op_sel_hi:[0,1]
	v_pk_mul_f32 v[26:27], v[90:91], v[50:51] op_sel_hi:[0,1]
	v_cvt_pk_bf16_f32 v24, v24, v25
	v_cvt_pk_bf16_f32 v25, v26, v27
	v_pk_mul_f32 v[26:27], v[90:91], v[60:61] op_sel_hi:[0,1]
	v_cvt_pk_bf16_f32 v26, v26, v27
	v_mul_f32_e32 v27, 0x4b800000, v40
	v_cmp_gt_f32_e32 vcc, s12, v40
	v_cvt_pk_bf16_f32 v57, v50, v51
	v_and_b32_e32 v51, 0xffff0000, v140
	v_cndmask_b32_e32 v27, v40, v27, vcc
	v_rsq_f32_e32 v50, v27
	v_pk_mul_f32 v[40:41], v[90:91], v[62:63] op_sel_hi:[0,1]
	v_cvt_pk_bf16_f32 v27, v40, v41
	global_store_dwordx4 v[48:49], v[24:27], off
	v_lshlrev_b32_e32 v48, 16, v141
	v_and_b32_e32 v49, 0xffff0000, v141
	v_mul_f32_e32 v24, 0x45800000, v50
	v_cndmask_b32_e32 v24, v50, v24, vcc
	v_mul_f32_e32 v24, 0x3db504f3, v24
	v_pk_mul_f32 v[26:27], v[32:33], v[24:25] op_sel_hi:[1,0]
	v_pk_mul_f32 v[32:33], v[42:43], v[24:25] op_sel_hi:[1,0]
	v_pk_mul_f32 v[34:35], v[34:35], v[24:25] op_sel_hi:[1,0]
	v_pk_mul_f32 v[40:41], v[108:109], v[24:25] op_sel_hi:[1,0]
	v_cvt_pk_bf16_f32 v64, v26, v27
	v_pk_mul_f32 v[24:25], v[96:97], v[26:27] op_sel_hi:[0,1]
	v_pk_mul_f32 v[26:27], v[96:97], v[32:33] op_sel_hi:[0,1]
	v_cvt_pk_bf16_f32 v66, v34, v35
	v_cvt_pk_bf16_f32 v24, v24, v25
	v_cvt_pk_bf16_f32 v25, v26, v27
	v_pk_mul_f32 v[26:27], v[96:97], v[34:35] op_sel_hi:[0,1]
	v_lshlrev_b32_e32 v34, 16, v198
	v_and_b32_e32 v35, 0xffff0000, v198
	v_cvt_pk_bf16_f32 v65, v32, v33
	v_cvt_pk_bf16_f32 v67, v40, v41
	v_pk_mul_f32 v[32:33], v[96:97], v[40:41] op_sel_hi:[0,1]
	s_waitcnt vmcnt(9)
	v_pk_fma_f32 v[34:35], v[6:7], v[34:35], 0 op_sel_hi:[1,1,0]
	v_lshlrev_b32_e32 v40, 16, v193
	v_and_b32_e32 v41, 0xffff0000, v193
	s_waitcnt vmcnt(7)
	v_pk_fma_f32 v[34:35], v[30:31], v[40:41], v[34:35]
	v_lshlrev_b32_e32 v108, 16, v191
	s_waitcnt vmcnt(5)
	v_pk_fma_f32 v[34:35], v[38:39], v[80:81], v[34:35]
	v_and_b32_e32 v109, 0xffff0000, v191
	s_waitcnt vmcnt(3)
	v_pk_fma_f32 v[34:35], v[46:47], v[108:109], v[34:35]
	v_cvt_pk_bf16_f32 v26, v26, v27
	v_mul_f32_e32 v42, 0xbfb8aa3b, v34
	v_mul_f32_e32 v43, 0xbfb8aa3b, v35
	v_cvt_pk_bf16_f32 v27, v32, v33
	v_or_b32_e32 v32, 3, v75
	v_exp_f32_e32 v42, v42
	v_exp_f32_e32 v43, v43
	v_mad_u64_u32 v[102:103], s[8:9], v32, s54, v[74:75]
	v_lshlrev_b32_e32 v32, 7, v32
	v_ashrrev_i32_e32 v33, 31, v32
	v_lshl_add_u64 v[32:33], v[32:33], 1, v[70:71]
	v_add_f32_e32 v42, 1.0, v42
	v_add_f32_e32 v43, 1.0, v43
	global_store_dwordx4 v[32:33], v[24:27], off
	v_rcp_f32_e32 v42, v42
	v_rcp_f32_e32 v43, v43
	v_lshlrev_b32_e32 v26, 16, v137
	v_and_b32_e32 v27, 0xffff0000, v137
	v_pk_fma_f32 v[26:27], v[2:3], v[26:27], 0 op_sel_hi:[1,1,0]
	v_lshlrev_b32_e32 v32, 16, v126
	v_and_b32_e32 v33, 0xffff0000, v126
	v_pk_fma_f32 v[48:49], v[4:5], v[48:49], 0 op_sel_hi:[1,1,0]
	v_lshlrev_b32_e32 v50, 16, v140
	v_pk_fma_f32 v[26:27], v[14:15], v[32:33], v[26:27]
	v_lshlrev_b32_e32 v126, 16, v127
	v_and_b32_e32 v127, 0xffff0000, v127
	v_pk_fma_f32 v[48:49], v[28:29], v[50:51], v[48:49]
	v_pk_fma_f32 v[26:27], v[18:19], v[126:127], v[26:27]
	v_pk_fma_f32 v[48:49], v[36:37], v[124:125], v[48:49]
	v_lshlrev_b32_e32 v110, 16, v138
	v_and_b32_e32 v111, 0xffff0000, v138
	v_pk_fma_f32 v[26:27], v[22:23], v[112:113], v[26:27]
	v_pk_fma_f32 v[48:49], v[44:45], v[110:111], v[48:49]
	v_pk_mul_f32 v[104:105], v[34:35], v[42:43]
	v_mul_f32_e32 v34, 0xbfb8aa3b, v26
	v_cvt_pk_bf16_f32 v58, v60, v61
	v_mul_f32_e32 v60, 0xbfb8aa3b, v48
	v_mul_f32_e32 v61, 0xbfb8aa3b, v49
	v_exp_f32_e32 v42, v34
	v_mul_f32_e32 v34, 0xbfb8aa3b, v27
	v_exp_f32_e32 v60, v60
	v_exp_f32_e32 v61, v61
	v_exp_f32_e32 v43, v34
	v_add_f32_e32 v42, 1.0, v42
	v_add_f32_e32 v60, 1.0, v60
	v_add_f32_e32 v61, 1.0, v61
	v_add_f32_e32 v43, 1.0, v43
	v_rcp_f32_e32 v60, v60
	v_rcp_f32_e32 v61, v61
	v_rcp_f32_e32 v42, v42
	v_rcp_f32_e32 v43, v43
	v_pk_fma_f32 v[40:41], v[6:7], v[40:41], 0 op_sel_hi:[1,1,0]
	v_lshlrev_b32_e32 v136, 16, v133
	v_pk_fma_f32 v[40:41], v[30:31], v[80:81], v[40:41]
	v_and_b32_e32 v137, 0xffff0000, v133
	v_pk_fma_f32 v[40:41], v[38:39], v[108:109], v[40:41]
	v_pk_mul_f32 v[82:83], v[48:49], v[60:61]
	v_pk_fma_f32 v[40:41], v[46:47], v[136:137], v[40:41]
	v_lshlrev_b32_e32 v48, 16, v135
	v_and_b32_e32 v49, 0xffff0000, v135
	v_pk_mul_f32 v[140:141], v[26:27], v[42:43]
	v_mul_f32_e32 v42, 0xbfb8aa3b, v40
	v_mul_f32_e32 v43, 0xbfb8aa3b, v41
	v_pk_fma_f32 v[48:49], v[0:1], v[48:49], 0 op_sel_hi:[1,1,0]
	v_lshlrev_b32_e32 v60, 16, v128
	v_and_b32_e32 v61, 0xffff0000, v128
	v_exp_f32_e32 v42, v42
	v_exp_f32_e32 v43, v43
	v_pk_fma_f32 v[48:49], v[12:13], v[60:61], v[48:49]
	v_lshlrev_b32_e32 v128, 16, v129
	v_and_b32_e32 v129, 0xffff0000, v129
	v_pk_fma_f32 v[48:49], v[16:17], v[128:129], v[48:49]
	v_lshlrev_b32_e32 v114, 16, v134
	v_and_b32_e32 v115, 0xffff0000, v134
	v_pk_fma_f32 v[48:49], v[20:21], v[114:115], v[48:49]
	v_cvt_pk_bf16_f32 v59, v62, v63
	v_mul_f32_e32 v62, 0xbfb8aa3b, v48
	v_mul_f32_e32 v63, 0xbfb8aa3b, v49
	v_add_f32_e32 v42, 1.0, v42
	v_add_f32_e32 v43, 1.0, v43
	v_exp_f32_e32 v62, v62
	v_exp_f32_e32 v63, v63
	v_rcp_f32_e32 v42, v42
	v_rcp_f32_e32 v43, v43
	v_add_f32_e32 v26, 1.0, v62
	v_add_f32_e32 v27, 1.0, v63
	v_rcp_f32_e32 v26, v26
	v_pk_mul_f32 v[106:107], v[40:41], v[42:43]
	v_pk_fma_f32 v[40:41], v[4:5], v[50:51], 0 op_sel_hi:[1,1,0]
	v_rcp_f32_e32 v27, v27
	v_pk_fma_f32 v[40:41], v[28:29], v[124:125], v[40:41]
	v_lshlrev_b32_e32 v134, 16, v132
	v_and_b32_e32 v135, 0xffff0000, v132
	v_pk_fma_f32 v[40:41], v[36:37], v[110:111], v[40:41]
	v_cvt_pk_bf16_f32 v52, v120, v121
	v_pk_fma_f32 v[40:41], v[44:45], v[134:135], v[40:41]
	v_pk_mul_f32 v[120:121], v[48:49], v[26:27]
	v_mul_f32_e32 v42, 0xbfb8aa3b, v40
	v_exp_f32_e32 v48, v42
	v_mul_f32_e32 v42, 0xbfb8aa3b, v41
	v_exp_f32_e32 v49, v42
	v_pk_fma_f32 v[32:33], v[2:3], v[32:33], 0 op_sel_hi:[1,1,0]
	v_add_f32_e32 v48, 1.0, v48
	v_rcp_f32_e32 v48, v48
	v_add_f32_e32 v49, 1.0, v49
	v_rcp_f32_e32 v49, v49
	v_pk_fma_f32 v[32:33], v[14:15], v[126:127], v[32:33]
	v_lshlrev_b32_e32 v132, 16, v130
	v_and_b32_e32 v133, 0xffff0000, v130
	v_pk_fma_f32 v[32:33], v[18:19], v[112:113], v[32:33]
	v_pk_mul_f32 v[116:117], v[40:41], v[48:49]
	v_pk_fma_f32 v[32:33], v[22:23], v[132:133], v[32:33]
	v_pk_fma_f32 v[48:49], v[0:1], v[60:61], 0 op_sel_hi:[1,1,0]
	v_mul_f32_e32 v50, 0xbfb8aa3b, v32
	v_mul_f32_e32 v51, 0xbfb8aa3b, v33
	v_exp_f32_e32 v50, v50
	v_exp_f32_e32 v51, v51
	v_pk_fma_f32 v[48:49], v[12:13], v[128:129], v[48:49]
	v_lshlrev_b32_e32 v130, 16, v131
	v_and_b32_e32 v131, 0xffff0000, v131
	v_pk_fma_f32 v[48:49], v[16:17], v[114:115], v[48:49]
	v_add_f32_e32 v40, 1.0, v50
	v_pk_fma_f32 v[48:49], v[20:21], v[130:131], v[48:49]
	v_add_f32_e32 v41, 1.0, v51
	v_mul_f32_e32 v50, 0xbfb8aa3b, v48
	v_mul_f32_e32 v51, 0xbfb8aa3b, v49
	v_exp_f32_e32 v50, v50
	v_exp_f32_e32 v51, v51
	v_rcp_f32_e32 v40, v40
	v_rcp_f32_e32 v41, v41
	v_add_f32_e32 v50, 1.0, v50
	v_add_f32_e32 v51, 1.0, v51
	v_rcp_f32_e32 v50, v50
	v_rcp_f32_e32 v51, v51
	v_cvt_pk_bf16_f32 v55, v122, v123
	v_cvt_pk_bf16_f32 v53, v118, v119
	v_pk_mul_f32 v[26:27], v[120:121], v[120:121]
	v_pk_mul_f32 v[122:123], v[48:49], v[50:51]
	v_pk_mul_f32 v[118:119], v[32:33], v[40:41]
	v_pk_mul_f32 v[40:41], v[122:123], v[122:123]
	v_pk_mul_f32 v[62:63], v[140:141], v[140:141]
	v_pk_mul_f32 v[32:33], v[118:119], v[118:119]
	v_mov_b32_e32 v48, v40
	v_mov_b32_e32 v49, v26
	v_mov_b32_e32 v26, v41
	v_pk_add_f32 v[26:27], v[48:49], v[26:27]
	v_mov_b32_e32 v40, v32
	v_mov_b32_e32 v41, v62
	v_pk_mul_f32 v[34:35], v[82:83], v[82:83]
	v_pk_mul_f32 v[60:61], v[116:117], v[116:117]
	v_pk_add_f32 v[26:27], v[40:41], v[26:27]
	v_mov_b32_e32 v62, v33
	v_pk_add_f32 v[26:27], v[62:63], v[26:27]
	v_mov_b32_e32 v32, v60
	v_mov_b32_e32 v33, v34
	v_pk_mul_f32 v[24:25], v[104:105], v[104:105]
	v_pk_mul_f32 v[42:43], v[106:107], v[106:107]
	v_pk_add_f32 v[26:27], v[32:33], v[26:27]
	v_mov_b32_e32 v34, v61
	v_pk_add_f32 v[26:27], v[34:35], v[26:27]
	v_mov_b32_e32 v32, v42
	v_mov_b32_e32 v33, v24
	v_pk_add_f32 v[26:27], v[32:33], v[26:27]
	v_mov_b32_e32 v24, v43
	v_pk_add_f32 v[24:25], v[24:25], v[26:27]
	ds_bpermute_b32 v27, v195, v25
	ds_bpermute_b32 v26, v195, v24
	v_add_u32_e32 v32, 0x400, v68
	v_ashrrev_i32_e32 v33, 31, v32
	v_lshl_add_u64 v[48:49], v[32:33], 2, s[80:81]
	v_pk_fma_f32 v[80:81], v[6:7], v[80:81], 0 op_sel_hi:[1,1,0]
	s_waitcnt lgkmcnt(0)
	v_pk_add_f32 v[34:35], v[24:25], v[26:27]
	ds_bpermute_b32 v41, v196, v35
	ds_bpermute_b32 v40, v196, v34
	v_add_co_u32_e32 v24, vcc, s15, v48
	v_pk_fma_f32 v[6:7], v[6:7], v[108:109], 0 op_sel_hi:[1,1,0]
	s_nop 0
	v_addc_co_u32_e32 v25, vcc, 0, v49, vcc
	s_waitcnt lgkmcnt(0)
	v_pk_add_f32 v[40:41], v[34:35], v[40:41]
	ds_bpermute_b32 v43, v197, v41
	ds_bpermute_b32 v42, v197, v40
	v_add_co_u32_e32 v34, vcc, s83, v48
	v_lshlrev_b32_e32 v192, 16, v143
	s_nop 0
	v_addc_co_u32_e32 v35, vcc, 0, v49, vcc
	s_waitcnt lgkmcnt(0)
	v_pk_add_f32 v[76:77], v[40:41], v[42:43]
	ds_bpermute_b32 v79, v161, v77
	ds_bpermute_b32 v78, v161, v76
	v_add_co_u32_e32 v40, vcc, s95, v48
	v_and_b32_e32 v193, 0xffff0000, v143
	v_pk_fma_f32 v[6:7], v[30:31], v[136:137], v[6:7]
	s_waitcnt lgkmcnt(0)
	v_pk_add_f32 v[76:77], v[76:77], v[78:79]
	v_addc_co_u32_e32 v41, vcc, 0, v49, vcc
	v_pk_add_f32 v[138:139], v[76:77], s[6:7] op_sel_hi:[1,0]
	v_lshlrev_b32_e32 v208, 16, v188
	v_and_b32_e32 v209, 0xffff0000, v188
	v_pk_fma_f32 v[6:7], v[38:39], v[192:193], v[6:7]
	v_mul_f32_e32 v76, 0x4b800000, v139
	v_cmp_gt_f32_e32 vcc, s12, v139
	v_pk_fma_f32 v[6:7], v[46:47], v[208:209], v[6:7]
	v_pk_fma_f32 v[80:81], v[30:31], v[108:109], v[80:81]
	v_cndmask_b32_e32 v76, v139, v76, vcc
	v_mul_f32_e32 v30, 0xbfb8aa3b, v6
	v_mul_f32_e32 v31, 0xbfb8aa3b, v7
	v_rsq_f32_e32 v84, v76
	v_exp_f32_e32 v30, v30
	v_exp_f32_e32 v31, v31
	v_pk_fma_f32 v[80:81], v[38:39], v[136:137], v[80:81]
	v_mul_f32_e32 v101, 0x45800000, v84
	v_pk_fma_f32 v[198:199], v[46:47], v[192:193], v[80:81]
	v_add_f32_e32 v30, 1.0, v30
	v_mul_f32_e32 v80, 0xbfb8aa3b, v198
	v_exp_f32_e32 v81, v80
	v_mul_f32_e32 v80, 0xbfb8aa3b, v199
	v_add_f32_e32 v31, 1.0, v31
	v_cndmask_b32_e32 v84, v84, v101, vcc
	v_exp_f32_e32 v101, v80
	v_pk_fma_f32 v[124:125], v[4:5], v[124:125], 0 op_sel_hi:[1,1,0]
	v_rcp_f32_e32 v30, v30
	v_rcp_f32_e32 v31, v31
	v_pk_fma_f32 v[124:125], v[28:29], v[110:111], v[124:125]
	v_lshlrev_b32_e32 v202, 16, v142
	v_and_b32_e32 v203, 0xffff0000, v142
	v_pk_fma_f32 v[124:125], v[36:37], v[134:135], v[124:125]
	v_pk_fma_f32 v[4:5], v[4:5], v[110:111], 0 op_sel_hi:[1,1,0]
	v_add_f32_e32 v81, 1.0, v81
	v_pk_fma_f32 v[142:143], v[44:45], v[202:203], v[124:125]
	v_pk_fma_f32 v[4:5], v[28:29], v[134:135], v[4:5]
	v_rcp_f32_e32 v200, v81
	v_add_f32_e32 v81, 1.0, v101
	v_mul_f32_e32 v101, 0xbfb8aa3b, v142
	v_pk_mul_f32 v[30:31], v[6:7], v[30:31]
	v_lshlrev_b32_e32 v6, 16, v187
	v_and_b32_e32 v7, 0xffff0000, v187
	v_pk_fma_f32 v[4:5], v[36:37], v[202:203], v[4:5]
	v_exp_f32_e32 v101, v101
	v_mul_f32_e32 v103, 0xbfb8aa3b, v143
	v_rcp_f32_e32 v201, v81
	v_pk_fma_f32 v[4:5], v[44:45], v[6:7], v[4:5]
	v_exp_f32_e32 v103, v103
	v_mul_f32_e32 v6, 0xbfb8aa3b, v4
	v_pk_fma_f32 v[126:127], v[2:3], v[126:127], 0 op_sel_hi:[1,1,0]
	v_exp_f32_e32 v28, v6
	v_mul_f32_e32 v6, 0xbfb8aa3b, v5
	v_pk_fma_f32 v[126:127], v[14:15], v[112:113], v[126:127]
	v_exp_f32_e32 v29, v6
	v_pk_fma_f32 v[2:3], v[2:3], v[112:113], 0 op_sel_hi:[1,1,0]
	v_add_f32_e32 v81, 1.0, v101
	v_pk_mul_f32 v[124:125], v[140:141], v[84:85] op_sel_hi:[1,0]
	v_pk_mul_f32 v[140:141], v[198:199], v[200:201]
	v_lshlrev_b32_e32 v200, 16, v190
	v_and_b32_e32 v201, 0xffff0000, v190
	v_pk_fma_f32 v[126:127], v[18:19], v[132:133], v[126:127]
	v_pk_fma_f32 v[2:3], v[14:15], v[132:133], v[2:3]
	v_rcp_f32_e32 v204, v81
	v_add_f32_e32 v81, 1.0, v103
	v_pk_fma_f32 v[126:127], v[22:23], v[200:201], v[126:127]
	v_lshlrev_b32_e32 v36, 16, v186
	v_and_b32_e32 v37, 0xffff0000, v186
	v_pk_fma_f32 v[2:3], v[18:19], v[200:201], v[2:3]
	v_rcp_f32_e32 v205, v81
	v_mul_f32_e32 v81, 0xbfb8aa3b, v126
	v_pk_fma_f32 v[2:3], v[22:23], v[36:37], v[2:3]
	v_exp_f32_e32 v81, v81
	v_mul_f32_e32 v101, 0xbfb8aa3b, v127
	v_add_f32_e32 v28, 1.0, v28
	v_add_f32_e32 v29, 1.0, v29
	v_mul_f32_e32 v14, 0xbfb8aa3b, v2
	v_mul_f32_e32 v15, 0xbfb8aa3b, v3
	v_exp_f32_e32 v101, v101
	v_rcp_f32_e32 v28, v28
	v_rcp_f32_e32 v29, v29
	v_exp_f32_e32 v14, v14
	v_exp_f32_e32 v15, v15
	v_pk_fma_f32 v[128:129], v[0:1], v[128:129], 0 op_sel_hi:[1,1,0]
	v_pk_fma_f32 v[0:1], v[0:1], v[114:115], 0 op_sel_hi:[1,1,0]
	v_pk_fma_f32 v[128:129], v[12:13], v[114:115], v[128:129]
	v_add_f32_e32 v81, 1.0, v81
	v_lshlrev_b32_e32 v206, 16, v189
	v_and_b32_e32 v207, 0xffff0000, v189
	v_pk_fma_f32 v[128:129], v[16:17], v[130:131], v[128:129]
	v_pk_fma_f32 v[0:1], v[12:13], v[130:131], v[0:1]
	v_pk_mul_f32 v[142:143], v[142:143], v[204:205]
	v_rcp_f32_e32 v204, v81
	v_add_f32_e32 v81, 1.0, v101
	v_pk_fma_f32 v[128:129], v[20:21], v[206:207], v[128:129]
	v_pk_mul_f32 v[22:23], v[4:5], v[28:29]
	v_add_f32_e32 v4, 1.0, v14
	v_add_f32_e32 v5, 1.0, v15
	v_lshlrev_b32_e32 v14, 16, v91
	v_and_b32_e32 v15, 0xffff0000, v91
	v_pk_fma_f32 v[0:1], v[16:17], v[206:207], v[0:1]
	v_rcp_f32_e32 v205, v81
	v_mul_f32_e32 v81, 0xbfb8aa3b, v128
	v_pk_fma_f32 v[0:1], v[20:21], v[14:15], v[0:1]
	v_exp_f32_e32 v81, v81
	v_mul_f32_e32 v101, 0xbfb8aa3b, v129
	v_mul_f32_e32 v12, 0xbfb8aa3b, v0
	v_mul_f32_e32 v13, 0xbfb8aa3b, v1
	v_exp_f32_e32 v101, v101
	v_exp_f32_e32 v12, v12
	v_exp_f32_e32 v13, v13
	v_add_f32_e32 v81, 1.0, v81
	v_pk_mul_f32 v[126:127], v[126:127], v[204:205]
	v_rcp_f32_e32 v204, v81
	v_add_f32_e32 v81, 1.0, v101
	v_add_f32_e32 v12, 1.0, v12
	v_add_f32_e32 v13, 1.0, v13
	v_rcp_f32_e32 v205, v81
	v_rcp_f32_e32 v12, v12
	v_rcp_f32_e32 v13, v13
	v_rcp_f32_e32 v4, v4
	v_rcp_f32_e32 v5, v5
	v_pk_mul_f32 v[46:47], v[128:129], v[204:205]
	v_pk_mul_f32 v[0:1], v[0:1], v[12:13]
	v_pk_mul_f32 v[108:109], v[46:47], v[46:47]
	v_pk_mul_f32 v[2:3], v[2:3], v[4:5]
	v_pk_mul_f32 v[12:13], v[0:1], v[0:1]
	v_pk_mul_f32 v[38:39], v[126:127], v[126:127]
	v_pk_mul_f32 v[4:5], v[2:3], v[2:3]
	v_mov_b32_e32 v16, v12
	v_mov_b32_e32 v17, v108
	v_mov_b32_e32 v108, v13
	v_pk_add_f32 v[12:13], v[16:17], v[108:109]
	v_mov_b32_e32 v16, v4
	v_mov_b32_e32 v17, v38
	v_pk_mul_f32 v[190:191], v[142:143], v[142:143]
	v_pk_mul_f32 v[14:15], v[22:23], v[22:23]
	v_pk_add_f32 v[12:13], v[16:17], v[12:13]
	v_mov_b32_e32 v38, v5
	v_pk_add_f32 v[4:5], v[38:39], v[12:13]
	v_mov_b32_e32 v12, v14
	v_mov_b32_e32 v13, v190
	v_pk_mul_f32 v[198:199], v[140:141], v[140:141]
	v_pk_mul_f32 v[6:7], v[30:31], v[30:31]
	v_pk_add_f32 v[4:5], v[12:13], v[4:5]
	v_mov_b32_e32 v190, v15
	v_pk_add_f32 v[4:5], v[190:191], v[4:5]
	v_mov_b32_e32 v12, v6
	v_mov_b32_e32 v13, v198
	v_pk_add_f32 v[4:5], v[12:13], v[4:5]
	v_mov_b32_e32 v198, v7
	v_pk_add_f32 v[12:13], v[198:199], v[4:5]
	ds_bpermute_b32 v15, v195, v13
	ds_bpermute_b32 v14, v195, v12
	v_lshl_add_u64 v[32:33], v[48:49], 0, s[28:29]
	global_load_dwordx4 v[60:63], v[24:25], off
	s_nop 0
	global_load_dwordx4 v[24:27], v[32:33], off offset:16
	v_lshl_add_u64 v[32:33], v[48:49], 0, s[36:37]
	v_lshl_add_u64 v[50:51], v[48:49], 0, s[38:39]
	s_waitcnt lgkmcnt(0)
	v_pk_add_f32 v[12:13], v[12:13], v[14:15]
	ds_bpermute_b32 v15, v196, v13
	ds_bpermute_b32 v14, v196, v12
	global_load_dwordx4 v[68:71], v[34:35], off
	s_nop 0
	global_load_dwordx4 v[32:35], v[32:33], off offset:16
	s_nop 0
	global_load_dwordx4 v[72:75], v[40:41], off
	s_nop 0
	global_load_dwordx4 v[40:43], v[50:51], off offset:16
	v_lshl_add_u64 v[50:51], v[48:49], 0, s[40:41]
	v_add_co_u32_e64 v48, s[42:43], s33, v48
	v_mul_f32_e32 v16, 0x4b800000, v138
	s_nop 0
	v_addc_co_u32_e64 v49, s[42:43], 0, v49, s[42:43]
	global_load_dwordx4 v[76:79], v[48:49], off
	s_nop 0
	global_load_dwordx4 v[48:51], v[50:51], off offset:16
	v_cmp_gt_f32_e32 vcc, s12, v138
	s_waitcnt lgkmcnt(0)
	v_pk_add_f32 v[12:13], v[12:13], v[14:15]
	ds_bpermute_b32 v15, v197, v13
	v_cndmask_b32_e32 v16, v138, v16, vcc
	ds_bpermute_b32 v14, v197, v12
	v_rsq_f32_e32 v16, v16
	v_pk_mul_f32 v[4:5], v[104:105], v[84:85] op_sel_hi:[1,0]
	v_pk_mul_f32 v[120:121], v[120:121], v[84:85] op_sel_hi:[1,0]
	v_pk_mul_f32 v[6:7], v[82:83], v[84:85] op_sel_hi:[1,0]
	v_mul_f32_e32 v17, 0x45800000, v16
	s_waitcnt lgkmcnt(0)
	v_pk_add_f32 v[12:13], v[12:13], v[14:15]
	v_cndmask_b32_e32 v18, v16, v17, vcc
	ds_bpermute_b32 v17, v161, v13
	ds_bpermute_b32 v16, v161, v12
	v_pk_mul_f32 v[28:29], v[122:123], v[18:19] op_sel_hi:[1,0]
	v_pk_mul_f32 v[44:45], v[118:119], v[18:19] op_sel_hi:[1,0]
	v_pk_mul_f32 v[104:105], v[116:117], v[18:19] op_sel_hi:[1,0]
	v_cvt_pk_bf16_f32 v11, v220, v221
	s_waitcnt lgkmcnt(0)
	v_pk_add_f32 v[12:13], v[12:13], v[16:17]
	v_cvt_pk_bf16_f32 v80, v120, v121
	v_pk_add_f32 v[20:21], v[12:13], s[6:7] op_sel_hi:[1,0]
	v_cvt_pk_bf16_f32 v81, v124, v125
	v_mul_f32_e32 v12, 0x4b800000, v21
	v_cmp_gt_f32_e32 vcc, s12, v21
	v_cvt_pk_bf16_f32 v82, v6, v7
	v_cvt_pk_bf16_f32 v83, v4, v5
	v_cndmask_b32_e32 v12, v21, v12, vcc
	v_rsq_f32_e32 v19, v12
	v_mul_f32_e32 v21, 0x4b800000, v20
	v_cvt_pk_bf16_f32 v14, v28, v29
	v_cvt_pk_bf16_f32 v15, v44, v45
	v_pk_mul_f32 v[12:13], v[106:107], v[18:19] op_sel_hi:[1,0]
	v_mul_f32_e32 v18, 0x45800000, v19
	v_cndmask_b32_e32 v36, v19, v18, vcc
	v_cmp_gt_f32_e32 vcc, s12, v20
	v_pk_mul_f32 v[46:47], v[46:47], v[36:37] op_sel_hi:[1,0]
	v_pk_mul_f32 v[106:107], v[126:127], v[36:37] op_sel_hi:[1,0]
	v_cndmask_b32_e32 v20, v20, v21, vcc
	v_pk_mul_f32 v[108:109], v[142:143], v[36:37] op_sel_hi:[1,0]
	v_rsq_f32_e32 v37, v20
	v_cvt_pk_bf16_f32 v16, v104, v105
	v_cvt_pk_bf16_f32 v17, v12, v13
	v_cvt_pk_bf16_f32 v18, v46, v47
	v_pk_mul_f32 v[110:111], v[140:141], v[36:37] op_sel_hi:[1,0]
	v_mul_f32_e32 v36, 0x45800000, v37
	v_cndmask_b32_e32 v84, v37, v36, vcc
	v_pk_mul_f32 v[112:113], v[0:1], v[84:85] op_sel_hi:[1,0]
	v_pk_mul_f32 v[114:115], v[2:3], v[84:85] op_sel_hi:[1,0]
	ds_read_b128 v[0:3], v87 offset:256
	v_pk_mul_f32 v[22:23], v[22:23], v[84:85] op_sel_hi:[1,0]
	v_pk_mul_f32 v[30:31], v[30:31], v[84:85] op_sel_hi:[1,0]
	v_cvt_pk_bf16_f32 v19, v106, v107
	v_cvt_pk_bf16_f32 v20, v108, v109
	v_cvt_pk_bf16_f32 v21, v110, v111
	v_cvt_pk_bf16_f32 v36, v112, v113
	v_cvt_pk_bf16_f32 v37, v114, v115
	v_cvt_pk_bf16_f32 v38, v22, v23
	v_cvt_pk_bf16_f32 v39, v30, v31
	v_mov_b32_e32 v116, v120
	v_mov_b32_e32 v117, v28
	ds_write_b128 v100, v[8:11] offset:17408
	ds_write_b128 v100, v[52:55] offset:17680
	ds_write_b128 v100, v[56:59] offset:17952
	ds_write_b128 v102, v[64:67] offset:17408
	ds_write_b128 v100, v[80:83]
	ds_write_b128 v100, v[14:17] offset:272
	ds_write_b128 v100, v[18:21] offset:544
	ds_write_b128 v102, v[36:39]
	v_mov_b32_e32 v8, v46
	v_mov_b32_e32 v9, v112
	s_waitcnt lgkmcnt(8)
	v_pk_mul_f32 v[118:119], v[0:1], v[116:117]
	v_mov_b32_e32 v87, v94
	v_pk_mul_f32 v[10:11], v[2:3], v[8:9]
	v_mov_b32_e32 v91, v96
	v_pk_mul_f32 v[118:119], v[86:87], v[118:119]
	v_pk_mul_f32 v[10:11], v[90:91], v[10:11]
	v_cvt_pk_bf16_f32 v118, v118, v119
	v_cvt_pk_bf16_f32 v119, v10, v11
	v_pk_mul_f32 v[10:11], v[88:89], v[116:117]
	v_pk_mul_f32 v[8:9], v[92:93], v[8:9]
	v_lshlrev_b32_e32 v84, 10, v151
	v_cvt_pk_bf16_f32 v10, v10, v11
	v_cvt_pk_bf16_f32 v11, v8, v9
	v_lshl_add_u64 v[8:9], v[98:99], 0, v[84:85]
	v_mov_b32_e32 v28, v121
	v_mov_b32_e32 v112, v47
	global_store_dwordx2 v[8:9], v[10:11], off
	v_pk_mul_f32 v[8:9], v[0:1], v[28:29]
	v_pk_mul_f32 v[10:11], v[2:3], v[112:113]
	v_pk_mul_f32 v[8:9], v[86:87], v[8:9]
	v_pk_mul_f32 v[10:11], v[90:91], v[10:11]
	v_or_b32_e32 v16, 1, v179
	v_cvt_pk_bf16_f32 v8, v8, v9
	v_cvt_pk_bf16_f32 v9, v10, v11
	v_pk_mul_f32 v[10:11], v[88:89], v[28:29]
	v_pk_mul_f32 v[14:15], v[92:93], v[112:113]
	v_cvt_pk_bf16_f32 v10, v10, v11
	v_cvt_pk_bf16_f32 v11, v14, v15
	v_lshlrev_b32_e32 v14, 7, v16
	v_mov_b32_e32 v15, v85
	v_lshl_add_u64 v[14:15], v[98:99], 0, v[14:15]
	v_mad_u32_u24 v21, v16, s13, v185
	global_store_dwordx2 v[14:15], v[10:11], off
	v_mov_b32_e32 v10, v124
	v_mov_b32_e32 v11, v44
	v_mov_b32_e32 v16, v106
	v_mov_b32_e32 v17, v114
	v_pk_mul_f32 v[14:15], v[0:1], v[10:11]
	v_pk_mul_f32 v[18:19], v[2:3], v[16:17]
	s_movk_i32 s8, 0x480
	v_pk_mul_f32 v[14:15], v[86:87], v[14:15]
	v_pk_mul_f32 v[18:19], v[90:91], v[18:19]
	v_mad_u32_u24 v20, v151, s8, v185
	v_cvt_pk_bf16_f32 v14, v14, v15
	v_cvt_pk_bf16_f32 v15, v18, v19
	v_add_u32_e32 v28, 0x8800, v21
	ds_write_b64 v20, v[118:119] offset:34816
	v_pk_mul_f32 v[10:11], v[88:89], v[10:11]
	v_pk_mul_f32 v[16:17], v[92:93], v[16:17]
	ds_write2_b64 v28, v[8:9], v[14:15] offset1:18
	v_or_b32_e32 v8, 0x100, v84
	v_mov_b32_e32 v9, v85
	v_cvt_pk_bf16_f32 v10, v10, v11
	v_cvt_pk_bf16_f32 v11, v16, v17
	v_lshl_add_u64 v[8:9], v[98:99], 0, v[8:9]
	v_mov_b32_e32 v44, v125
	v_mov_b32_e32 v114, v107
	global_store_dwordx2 v[8:9], v[10:11], off
	v_pk_mul_f32 v[8:9], v[0:1], v[44:45]
	v_pk_mul_f32 v[10:11], v[2:3], v[114:115]
	v_pk_mul_f32 v[8:9], v[86:87], v[8:9]
	v_pk_mul_f32 v[10:11], v[90:91], v[10:11]
	v_cvt_pk_bf16_f32 v8, v8, v9
	v_cvt_pk_bf16_f32 v9, v10, v11
	v_pk_mul_f32 v[10:11], v[88:89], v[44:45]
	v_pk_mul_f32 v[14:15], v[92:93], v[114:115]
	v_cvt_pk_bf16_f32 v10, v10, v11
	v_cvt_pk_bf16_f32 v11, v14, v15
	v_or_b32_e32 v14, 0x180, v84
	v_mov_b32_e32 v15, v85
	v_lshl_add_u64 v[14:15], v[98:99], 0, v[14:15]
	global_store_dwordx2 v[14:15], v[10:11], off
	v_mov_b32_e32 v10, v6
	v_mov_b32_e32 v11, v104
	v_mov_b32_e32 v16, v108
	v_mov_b32_e32 v17, v22
	v_pk_mul_f32 v[14:15], v[0:1], v[10:11]
	v_pk_mul_f32 v[18:19], v[2:3], v[16:17]
	v_pk_mul_f32 v[14:15], v[86:87], v[14:15]
	v_pk_mul_f32 v[18:19], v[90:91], v[18:19]
	v_cvt_pk_bf16_f32 v14, v14, v15
	v_cvt_pk_bf16_f32 v15, v18, v19
	v_pk_mul_f32 v[10:11], v[88:89], v[10:11]
	v_pk_mul_f32 v[16:17], v[92:93], v[16:17]
	ds_write2_b64 v28, v[8:9], v[14:15] offset0:36 offset1:54
	v_or_b32_e32 v8, 0x200, v84
	v_mov_b32_e32 v9, v85
	v_cvt_pk_bf16_f32 v10, v10, v11
	v_cvt_pk_bf16_f32 v11, v16, v17
	v_lshl_add_u64 v[8:9], v[98:99], 0, v[8:9]
	v_mov_b32_e32 v104, v7
	v_mov_b32_e32 v22, v109
	global_store_dwordx2 v[8:9], v[10:11], off
	v_pk_mul_f32 v[6:7], v[0:1], v[104:105]
	v_pk_mul_f32 v[8:9], v[2:3], v[22:23]
	v_pk_mul_f32 v[6:7], v[86:87], v[6:7]
	v_pk_mul_f32 v[8:9], v[90:91], v[8:9]
	v_cvt_pk_bf16_f32 v6, v6, v7
	v_cvt_pk_bf16_f32 v7, v8, v9
	v_pk_mul_f32 v[8:9], v[88:89], v[104:105]
	v_pk_mul_f32 v[10:11], v[92:93], v[22:23]
	v_cvt_pk_bf16_f32 v8, v8, v9
	v_cvt_pk_bf16_f32 v9, v10, v11
	v_or_b32_e32 v10, 0x280, v84
	v_mov_b32_e32 v11, v85
	v_lshl_add_u64 v[10:11], v[98:99], 0, v[10:11]
	global_store_dwordx2 v[10:11], v[8:9], off
	v_mov_b32_e32 v8, v4
	v_mov_b32_e32 v9, v12
	v_mov_b32_e32 v14, v110
	v_mov_b32_e32 v15, v30
	v_pk_mul_f32 v[10:11], v[0:1], v[8:9]
	v_pk_mul_f32 v[16:17], v[2:3], v[14:15]
	v_pk_mul_f32 v[10:11], v[86:87], v[10:11]
	v_pk_mul_f32 v[16:17], v[90:91], v[16:17]
	v_cvt_pk_bf16_f32 v10, v10, v11
	v_cvt_pk_bf16_f32 v11, v16, v17
	v_pk_mul_f32 v[8:9], v[88:89], v[8:9]
	v_pk_mul_f32 v[14:15], v[92:93], v[14:15]
	ds_write2_b64 v28, v[6:7], v[10:11] offset0:72 offset1:90
	v_or_b32_e32 v6, 0x300, v84
	v_mov_b32_e32 v7, v85
	v_cvt_pk_bf16_f32 v8, v8, v9
	v_cvt_pk_bf16_f32 v9, v14, v15
	v_lshl_add_u64 v[6:7], v[98:99], 0, v[6:7]
	v_mov_b32_e32 v12, v5
	v_mov_b32_e32 v30, v111
	global_store_dwordx2 v[6:7], v[8:9], off
	v_pk_mul_f32 v[4:5], v[0:1], v[12:13]
	v_pk_mul_f32 v[6:7], v[2:3], v[30:31]
	v_pk_mul_f32 v[4:5], v[86:87], v[4:5]
	v_pk_mul_f32 v[6:7], v[90:91], v[6:7]
	v_cvt_pk_bf16_f32 v4, v4, v5
	v_cvt_pk_bf16_f32 v5, v6, v7
	v_pk_mul_f32 v[6:7], v[88:89], v[12:13]
	v_pk_mul_f32 v[8:9], v[92:93], v[30:31]
	v_lshlrev_b32_e32 v11, 16, v181
	v_lshlrev_b32_e32 v10, 16, v180
	v_cvt_pk_bf16_f32 v6, v6, v7
	v_cvt_pk_bf16_f32 v7, v8, v9
	v_lshlrev_b32_e32 v9, 16, v183
	v_mov_b32_e32 v8, v11
	s_waitcnt vmcnt(14)
	v_pk_fma_f32 v[14:15], v[60:61], v[10:11], 0 op_sel_hi:[0,1,0]
	ds_write_b64 v21, v[4:5] offset:35680
	v_lshlrev_b32_e32 v5, 16, v184
	v_mov_b32_e32 v4, v9
	s_waitcnt vmcnt(12)
	v_pk_fma_f32 v[14:15], v[68:69], v[8:9], v[14:15] op_sel_hi:[0,1,1]
	v_lshlrev_b32_e32 v13, 16, v182
	v_mov_b32_e32 v12, v5
	s_waitcnt vmcnt(10)
	v_pk_fma_f32 v[4:5], v[72:73], v[4:5], v[14:15] op_sel_hi:[0,1,1]
	s_waitcnt vmcnt(8)
	v_pk_fma_f32 v[4:5], v[76:77], v[12:13], v[4:5] op_sel_hi:[0,1,1]
	v_mul_f32_e32 v12, 0xbfb8aa3b, v5
	v_exp_f32_e32 v12, v12
	v_mul_f32_e32 v13, 0xbfb8aa3b, v4
	v_exp_f32_e32 v14, v13
	v_lshlrev_b32_e32 v15, 16, v178
	v_add_f32_e32 v12, 1.0, v12
	v_rcp_f32_e32 v13, v12
	v_add_f32_e32 v12, 1.0, v14
	v_lshlrev_b32_e32 v14, 16, v177
	v_pk_fma_f32 v[16:17], v[60:61], v[14:15], 0 op_sel_hi:[0,1,0]
	v_pk_mov_b32 v[14:15], v[14:15], v[10:11] op_sel:[1,0]
	v_rcp_f32_e32 v12, v12
	v_pk_fma_f32 v[14:15], v[68:69], v[14:15], v[16:17] op_sel_hi:[0,1,1]
	v_pk_fma_f32 v[10:11], v[72:73], v[10:11], v[14:15] op_sel_hi:[0,1,1]
	v_pk_fma_f32 v[8:9], v[76:77], v[8:9], v[10:11] op_sel_hi:[0,1,1]
	v_mul_f32_e32 v10, 0xbfb8aa3b, v9
	v_exp_f32_e32 v10, v10
	v_mul_f32_e32 v11, 0xbfb8aa3b, v8
	v_exp_f32_e32 v14, v11
	v_or_b32_e32 v84, 0x380, v84
	v_add_f32_e32 v10, 1.0, v10
	v_rcp_f32_e32 v11, v10
	v_add_f32_e32 v10, 1.0, v14
	v_rcp_f32_e32 v10, v10
	v_lshl_add_u64 v[14:15], v[98:99], 0, v[84:85]
	global_store_dwordx2 v[14:15], v[6:7], off
	v_pk_mul_f32 v[4:5], v[4:5], v[12:13]
	v_pk_mul_f32 v[6:7], v[8:9], v[10:11]
	v_and_b32_e32 v10, 0xffff0000, v181
	v_and_b32_e32 v8, 0xffff0000, v183
	v_and_b32_e32 v12, 0xffff0000, v180
	v_mov_b32_e32 v13, v10
	v_mov_b32_e32 v11, v8
	v_pk_fma_f32 v[16:17], v[60:61], v[12:13], 0 op_sel:[1,0,0] op_sel_hi:[1,1,0]
	v_and_b32_e32 v9, 0xffff0000, v184
	v_pk_fma_f32 v[16:17], v[68:69], v[10:11], v[16:17] op_sel:[1,0,0]
	v_and_b32_e32 v15, 0xffff0000, v182
	v_mov_b32_e32 v14, v9
	v_pk_fma_f32 v[8:9], v[72:73], v[8:9], v[16:17] op_sel:[1,0,0]
	v_pk_mul_f32 v[6:7], v[0:1], v[6:7]
	v_pk_fma_f32 v[8:9], v[76:77], v[14:15], v[8:9] op_sel:[1,0,0]
	v_cvt_pk_bf16_f32 v6, v6, v7
	v_mul_f32_e32 v14, 0xbfb8aa3b, v9
	v_exp_f32_e32 v14, v14
	v_mul_f32_e32 v15, 0xbfb8aa3b, v8
	v_exp_f32_e32 v16, v15
	v_and_b32_e32 v17, 0xffff0000, v178
	v_add_f32_e32 v7, 1.0, v14
	v_rcp_f32_e32 v15, v7
	v_add_f32_e32 v7, 1.0, v16
	v_and_b32_e32 v16, 0xffff0000, v177
	v_pk_fma_f32 v[18:19], v[60:61], v[16:17], 0 op_sel:[1,0,0] op_sel_hi:[1,1,0]
	v_pk_mov_b32 v[16:17], v[16:17], v[12:13] op_sel:[1,0]
	v_rcp_f32_e32 v14, v7
	v_pk_fma_f32 v[16:17], v[68:69], v[16:17], v[18:19] op_sel:[1,0,0]
	v_pk_mul_f32 v[4:5], v[2:3], v[4:5]
	v_pk_fma_f32 v[12:13], v[72:73], v[12:13], v[16:17] op_sel:[1,0,0]
	v_add_u32_e32 v30, 0xd000, v20
	v_pk_fma_f32 v[10:11], v[76:77], v[10:11], v[12:13] op_sel:[1,0,0]
	v_mov_b32_e32 v22, v63
	v_mul_f32_e32 v12, 0xbfb8aa3b, v11
	v_exp_f32_e32 v12, v12
	v_mul_f32_e32 v13, 0xbfb8aa3b, v10
	v_exp_f32_e32 v16, v13
	v_mov_b32_e32 v20, v71
	v_add_f32_e32 v7, 1.0, v12
	v_rcp_f32_e32 v13, v7
	v_add_f32_e32 v7, 1.0, v16
	v_rcp_f32_e32 v12, v7
	v_cvt_pk_bf16_f32 v7, v4, v5
	v_pk_mul_f32 v[4:5], v[8:9], v[14:15]
	v_lshlrev_b32_e32 v15, 16, v173
	v_pk_mul_f32 v[8:9], v[10:11], v[12:13]
	v_lshlrev_b32_e32 v12, 16, v174
	v_lshlrev_b32_e32 v14, 16, v172
	v_lshlrev_b32_e32 v10, 16, v175
	v_mov_b32_e32 v16, v15
	v_mov_b32_e32 v17, v12
	v_pk_fma_f32 v[18:19], v[62:63], v[14:15], 0 op_sel_hi:[0,1,0]
	v_mov_b32_e32 v13, v10
	v_pk_fma_f32 v[18:19], v[70:71], v[16:17], v[18:19] op_sel_hi:[0,1,1]
	v_lshlrev_b32_e32 v11, 16, v176
	v_pk_fma_f32 v[12:13], v[74:75], v[12:13], v[18:19] op_sel_hi:[0,1,1]
	v_pk_mul_f32 v[8:9], v[0:1], v[8:9]
	v_pk_fma_f32 v[10:11], v[78:79], v[10:11], v[12:13] op_sel_hi:[0,1,1]
	v_cvt_pk_bf16_f32 v8, v8, v9
	v_mul_f32_e32 v9, 0xbfb8aa3b, v11
	v_exp_f32_e32 v12, v9
	v_mul_f32_e32 v9, 0xbfb8aa3b, v10
	v_exp_f32_e32 v13, v9
	v_pk_mul_f32 v[4:5], v[2:3], v[4:5]
	s_nop 0
	v_cvt_pk_bf16_f32 v9, v4, v5
	v_add_f32_e32 v4, 1.0, v12
	v_rcp_f32_e32 v5, v4
	v_add_f32_e32 v4, 1.0, v13
	v_lshlrev_b32_e32 v13, 16, v171
	v_lshlrev_b32_e32 v12, 16, v170
	v_pk_fma_f32 v[18:19], v[62:63], v[12:13], 0 op_sel_hi:[0,1,0]
	v_pk_mov_b32 v[12:13], v[12:13], v[14:15] op_sel:[1,0]
	v_rcp_f32_e32 v4, v4
	v_pk_fma_f32 v[12:13], v[70:71], v[12:13], v[18:19] op_sel_hi:[0,1,1]
	v_pk_fma_f32 v[12:13], v[74:75], v[14:15], v[12:13] op_sel_hi:[0,1,1]
	v_pk_fma_f32 v[12:13], v[78:79], v[16:17], v[12:13] op_sel_hi:[0,1,1]
	v_mul_f32_e32 v14, 0xbfb8aa3b, v13
	v_exp_f32_e32 v14, v14
	v_mul_f32_e32 v15, 0xbfb8aa3b, v12
	v_exp_f32_e32 v16, v15
	ds_write2_b64 v30, v[6:7], v[8:9] offset1:18
	v_add_f32_e32 v14, 1.0, v14
	v_rcp_f32_e32 v15, v14
	v_add_f32_e32 v14, 1.0, v16
	v_rcp_f32_e32 v14, v14
	v_pk_mul_f32 v[4:5], v[10:11], v[4:5]
	v_and_b32_e32 v10, 0xffff0000, v174
	v_and_b32_e32 v8, 0xffff0000, v175
	v_pk_mul_f32 v[6:7], v[12:13], v[14:15]
	v_and_b32_e32 v12, 0xffff0000, v173
	v_and_b32_e32 v14, 0xffff0000, v172
	v_mov_b32_e32 v15, v12
	v_mov_b32_e32 v13, v10
	v_pk_fma_f32 v[28:29], v[22:23], v[14:15], 0 op_sel_hi:[0,1,0]
	v_mov_b32_e32 v11, v8
	v_mov_b32_e32 v18, v75
	v_pk_fma_f32 v[28:29], v[20:21], v[12:13], v[28:29] op_sel_hi:[0,1,1]
	v_and_b32_e32 v9, 0xffff0000, v176
	v_mov_b32_e32 v16, v79
	v_pk_fma_f32 v[10:11], v[18:19], v[10:11], v[28:29] op_sel_hi:[0,1,1]
	v_pk_fma_f32 v[8:9], v[16:17], v[8:9], v[10:11] op_sel_hi:[0,1,1]
	v_mul_f32_e32 v11, 0xbfb8aa3b, v8
	v_mul_f32_e32 v10, 0xbfb8aa3b, v9
	v_exp_f32_e32 v17, v11
	v_and_b32_e32 v29, 0xffff0000, v171
	v_and_b32_e32 v28, 0xffff0000, v170
	v_exp_f32_e32 v10, v10
	v_pk_fma_f32 v[22:23], v[22:23], v[28:29], 0 op_sel_hi:[0,1,0]
	v_pk_mov_b32 v[28:29], v[28:29], v[14:15] op_sel:[1,0]
	v_pk_mul_f32 v[6:7], v[0:1], v[6:7]
	v_pk_fma_f32 v[20:21], v[20:21], v[28:29], v[22:23] op_sel_hi:[0,1,1]
	v_pk_fma_f32 v[14:15], v[18:19], v[14:15], v[20:21] op_sel_hi:[0,1,1]
	v_pk_fma_f32 v[12:13], v[16:17], v[12:13], v[14:15] op_sel_hi:[0,1,1]
	v_cvt_pk_bf16_f32 v6, v6, v7
	v_add_f32_e32 v7, 1.0, v10
	v_mul_f32_e32 v10, 0xbfb8aa3b, v13
	v_exp_f32_e32 v14, v10
	v_mul_f32_e32 v10, 0xbfb8aa3b, v12
	v_exp_f32_e32 v16, v10
	v_rcp_f32_e32 v11, v7
	v_add_f32_e32 v7, 1.0, v17
	v_rcp_f32_e32 v10, v7
	v_add_f32_e32 v7, 1.0, v14
	v_rcp_f32_e32 v15, v7
	v_add_f32_e32 v7, 1.0, v16
	v_rcp_f32_e32 v14, v7
	v_pk_mul_f32 v[4:5], v[2:3], v[4:5]
	v_mov_b32_e32 v22, v27
	v_cvt_pk_bf16_f32 v7, v4, v5
	v_pk_mul_f32 v[4:5], v[8:9], v[10:11]
	v_pk_mul_f32 v[8:9], v[12:13], v[14:15]
	v_lshlrev_b32_e32 v12, 16, v167
	v_lshlrev_b32_e32 v15, 16, v166
	v_lshlrev_b32_e32 v14, 16, v165
	v_lshlrev_b32_e32 v10, 16, v168
	v_mov_b32_e32 v16, v15
	v_mov_b32_e32 v17, v12
	v_pk_fma_f32 v[18:19], v[24:25], v[14:15], 0 op_sel_hi:[0,1,0]
	v_mov_b32_e32 v13, v10
	v_pk_fma_f32 v[18:19], v[32:33], v[16:17], v[18:19] op_sel_hi:[0,1,1]
	v_lshlrev_b32_e32 v11, 16, v169
	v_pk_fma_f32 v[12:13], v[40:41], v[12:13], v[18:19] op_sel_hi:[0,1,1]
	v_pk_mul_f32 v[8:9], v[0:1], v[8:9]
	s_waitcnt vmcnt(8)
	v_pk_fma_f32 v[10:11], v[48:49], v[10:11], v[12:13] op_sel_hi:[0,1,1]
	v_cvt_pk_bf16_f32 v8, v8, v9
	v_mul_f32_e32 v9, 0xbfb8aa3b, v11
	v_exp_f32_e32 v9, v9
	v_mul_f32_e32 v12, 0xbfb8aa3b, v10
	v_lshlrev_b32_e32 v19, 16, v164
	v_lshlrev_b32_e32 v18, 16, v163
	v_exp_f32_e32 v12, v12
	v_pk_fma_f32 v[20:21], v[24:25], v[18:19], 0 op_sel_hi:[0,1,0]
	v_pk_mov_b32 v[18:19], v[18:19], v[14:15] op_sel:[1,0]
	v_add_f32_e32 v9, 1.0, v9
	v_pk_fma_f32 v[18:19], v[32:33], v[18:19], v[20:21] op_sel_hi:[0,1,1]
	v_pk_fma_f32 v[14:15], v[40:41], v[14:15], v[18:19] op_sel_hi:[0,1,1]
	v_pk_fma_f32 v[14:15], v[48:49], v[16:17], v[14:15] op_sel_hi:[0,1,1]
	v_rcp_f32_e32 v13, v9
	v_add_f32_e32 v9, 1.0, v12
	v_mul_f32_e32 v12, 0xbfb8aa3b, v15
	v_exp_f32_e32 v16, v12
	v_mul_f32_e32 v12, 0xbfb8aa3b, v14
	v_exp_f32_e32 v18, v12
	v_rcp_f32_e32 v12, v9
	v_add_f32_e32 v9, 1.0, v16
	v_rcp_f32_e32 v17, v9
	v_add_f32_e32 v9, 1.0, v18
	v_rcp_f32_e32 v16, v9
	v_pk_mul_f32 v[4:5], v[2:3], v[4:5]
	s_nop 0
	v_cvt_pk_bf16_f32 v9, v4, v5
	v_pk_mul_f32 v[4:5], v[10:11], v[12:13]
	v_and_b32_e32 v12, 0xffff0000, v166
	ds_write2_b64 v30, v[6:7], v[8:9] offset0:36 offset1:54
	v_pk_mul_f32 v[6:7], v[14:15], v[16:17]
	v_and_b32_e32 v10, 0xffff0000, v167
	v_and_b32_e32 v14, 0xffff0000, v165
	v_mov_b32_e32 v15, v12
	v_and_b32_e32 v8, 0xffff0000, v168
	v_mov_b32_e32 v13, v10
	v_pk_fma_f32 v[16:17], v[24:25], v[14:15], 0 op_sel:[1,0,0] op_sel_hi:[1,1,0]
	v_mov_b32_e32 v11, v8
	v_pk_fma_f32 v[16:17], v[32:33], v[12:13], v[16:17] op_sel:[1,0,0]
	v_and_b32_e32 v9, 0xffff0000, v169
	v_pk_fma_f32 v[10:11], v[40:41], v[10:11], v[16:17] op_sel:[1,0,0]
	v_pk_mul_f32 v[6:7], v[0:1], v[6:7]
	v_pk_fma_f32 v[8:9], v[48:49], v[8:9], v[10:11] op_sel:[1,0,0]
	v_cvt_pk_bf16_f32 v6, v6, v7
	v_mul_f32_e32 v10, 0xbfb8aa3b, v9
	v_exp_f32_e32 v10, v10
	v_mul_f32_e32 v11, 0xbfb8aa3b, v8
	v_exp_f32_e32 v16, v11
	v_and_b32_e32 v17, 0xffff0000, v164
	v_add_f32_e32 v7, 1.0, v10
	v_rcp_f32_e32 v11, v7
	v_add_f32_e32 v7, 1.0, v16
	v_and_b32_e32 v16, 0xffff0000, v163
	v_pk_fma_f32 v[18:19], v[24:25], v[16:17], 0 op_sel:[1,0,0] op_sel_hi:[1,1,0]
	v_pk_mov_b32 v[16:17], v[16:17], v[14:15] op_sel:[1,0]
	v_pk_mul_f32 v[4:5], v[2:3], v[4:5]
	v_pk_fma_f32 v[16:17], v[32:33], v[16:17], v[18:19] op_sel:[1,0,0]
	s_nop 0
	v_pk_fma_f32 v[14:15], v[40:41], v[14:15], v[16:17] op_sel:[1,0,0]
	s_nop 0
	v_pk_fma_f32 v[12:13], v[48:49], v[12:13], v[14:15] op_sel:[1,0,0]
	s_nop 0
	v_mul_f32_e32 v10, 0xbfb8aa3b, v13
	v_exp_f32_e32 v14, v10
	v_mul_f32_e32 v10, 0xbfb8aa3b, v12
	v_exp_f32_e32 v16, v10
	v_rcp_f32_e32 v10, v7
	v_add_f32_e32 v7, 1.0, v14
	v_rcp_f32_e32 v15, v7
	v_add_f32_e32 v7, 1.0, v16
	v_rcp_f32_e32 v14, v7
	v_cvt_pk_bf16_f32 v7, v4, v5
	v_pk_mul_f32 v[4:5], v[8:9], v[10:11]
	v_lshlrev_b32_e32 v10, 16, v158
	v_pk_mul_f32 v[8:9], v[12:13], v[14:15]
	v_lshlrev_b32_e32 v12, 16, v157
	v_lshlrev_b32_e32 v15, 16, v156
	v_lshlrev_b32_e32 v14, 16, v155
	v_mov_b32_e32 v16, v15
	v_mov_b32_e32 v17, v12
	v_pk_fma_f32 v[18:19], v[26:27], v[14:15], 0 op_sel_hi:[0,1,0]
	v_mov_b32_e32 v13, v10
	v_pk_fma_f32 v[18:19], v[34:35], v[16:17], v[18:19] op_sel_hi:[0,1,1]
	v_lshlrev_b32_e32 v11, 16, v162
	v_pk_fma_f32 v[12:13], v[42:43], v[12:13], v[18:19] op_sel_hi:[0,1,1]
	v_pk_mul_f32 v[8:9], v[0:1], v[8:9]
	v_pk_fma_f32 v[10:11], v[50:51], v[10:11], v[12:13] op_sel_hi:[0,1,1]
	v_cvt_pk_bf16_f32 v8, v8, v9
	v_mul_f32_e32 v9, 0xbfb8aa3b, v11
	v_exp_f32_e32 v9, v9
	v_mul_f32_e32 v12, 0xbfb8aa3b, v10
	v_lshlrev_b32_e32 v19, 16, v154
	v_lshlrev_b32_e32 v18, 16, v153
	v_exp_f32_e32 v12, v12
	v_pk_fma_f32 v[20:21], v[26:27], v[18:19], 0 op_sel_hi:[0,1,0]
	v_pk_mov_b32 v[18:19], v[18:19], v[14:15] op_sel:[1,0]
	v_add_f32_e32 v9, 1.0, v9
	v_pk_fma_f32 v[18:19], v[34:35], v[18:19], v[20:21] op_sel_hi:[0,1,1]
	v_pk_fma_f32 v[14:15], v[42:43], v[14:15], v[18:19] op_sel_hi:[0,1,1]
	v_pk_fma_f32 v[14:15], v[50:51], v[16:17], v[14:15] op_sel_hi:[0,1,1]
	v_rcp_f32_e32 v13, v9
	v_add_f32_e32 v9, 1.0, v12
	v_mul_f32_e32 v12, 0xbfb8aa3b, v15
	v_exp_f32_e32 v16, v12
	v_mul_f32_e32 v12, 0xbfb8aa3b, v14
	v_exp_f32_e32 v18, v12
	v_rcp_f32_e32 v12, v9
	v_add_f32_e32 v9, 1.0, v16
	v_rcp_f32_e32 v17, v9
	v_add_f32_e32 v9, 1.0, v18
	v_rcp_f32_e32 v16, v9
	v_pk_mul_f32 v[4:5], v[2:3], v[4:5]
	v_mov_b32_e32 v20, v35
	v_cvt_pk_bf16_f32 v9, v4, v5
	v_pk_mul_f32 v[4:5], v[10:11], v[12:13]
	v_and_b32_e32 v12, 0xffff0000, v156
	ds_write2_b64 v30, v[6:7], v[8:9] offset0:72 offset1:90
	v_pk_mul_f32 v[6:7], v[14:15], v[16:17]
	v_and_b32_e32 v10, 0xffff0000, v157
	v_and_b32_e32 v14, 0xffff0000, v155
	v_mov_b32_e32 v15, v12
	v_and_b32_e32 v8, 0xffff0000, v158
	v_mov_b32_e32 v13, v10
	v_pk_fma_f32 v[24:25], v[22:23], v[14:15], 0 op_sel_hi:[0,1,0]
	v_mov_b32_e32 v11, v8
	v_mov_b32_e32 v18, v43
	v_pk_fma_f32 v[24:25], v[20:21], v[12:13], v[24:25] op_sel_hi:[0,1,1]
	v_and_b32_e32 v9, 0xffff0000, v162
	v_mov_b32_e32 v16, v51
	v_pk_fma_f32 v[10:11], v[18:19], v[10:11], v[24:25] op_sel_hi:[0,1,1]
	v_pk_fma_f32 v[8:9], v[16:17], v[8:9], v[10:11] op_sel_hi:[0,1,1]
	v_mul_f32_e32 v11, 0xbfb8aa3b, v8
	v_mul_f32_e32 v10, 0xbfb8aa3b, v9
	v_exp_f32_e32 v17, v11
	v_and_b32_e32 v25, 0xffff0000, v154
	v_and_b32_e32 v24, 0xffff0000, v153
	v_exp_f32_e32 v10, v10
	v_pk_fma_f32 v[22:23], v[22:23], v[24:25], 0 op_sel_hi:[0,1,0]
	v_pk_mov_b32 v[24:25], v[24:25], v[14:15] op_sel:[1,0]
	v_pk_mul_f32 v[6:7], v[0:1], v[6:7]
	v_pk_fma_f32 v[20:21], v[20:21], v[24:25], v[22:23] op_sel_hi:[0,1,1]
	v_pk_fma_f32 v[14:15], v[18:19], v[14:15], v[20:21] op_sel_hi:[0,1,1]
	v_pk_fma_f32 v[12:13], v[16:17], v[12:13], v[14:15] op_sel_hi:[0,1,1]
	v_cvt_pk_bf16_f32 v6, v6, v7
	v_add_f32_e32 v7, 1.0, v10
	v_mul_f32_e32 v10, 0xbfb8aa3b, v13
	v_exp_f32_e32 v14, v10
	v_mul_f32_e32 v10, 0xbfb8aa3b, v12
	v_exp_f32_e32 v16, v10
	v_rcp_f32_e32 v11, v7
	v_add_f32_e32 v7, 1.0, v17
	v_rcp_f32_e32 v10, v7
	v_add_f32_e32 v7, 1.0, v14
	v_rcp_f32_e32 v15, v7
	v_add_f32_e32 v7, 1.0, v16
	v_rcp_f32_e32 v14, v7
	v_pk_mul_f32 v[4:5], v[2:3], v[4:5]
	v_and_b32_e32 v24, -16, v152
	v_cvt_pk_bf16_f32 v7, v4, v5
	v_pk_mul_f32 v[4:5], v[8:9], v[10:11]
	v_pk_mul_f32 v[8:9], v[12:13], v[14:15]
	v_pk_mul_f32 v[2:3], v[2:3], v[4:5]
	v_pk_mul_f32 v[0:1], v[0:1], v[8:9]
	v_add_u32_e32 v26, s19, v24
	v_cvt_pk_bf16_f32 v0, v0, v1
	v_cvt_pk_bf16_f32 v1, v2, v3
	v_mad_u32_u24 v29, v151, s54, v26
	ds_write2_b64 v30, v[6:7], v[0:1] offset0:108 offset1:126
	s_waitcnt lgkmcnt(0)
	s_barrier
	ds_read_b128 v[12:15], v29
	v_or_b32_e32 v27, s10, v151
	v_mad_u32_u24 v0, v27, s54, v148
	v_add_u32_e32 v25, v0, v24
	ds_read_b128 v[4:7], v25 offset:17408
	ds_read_b128 v[16:19], v29 offset:64
	ds_read_b128 v[8:11], v25 offset:17472
	v_lshl_add_u32 v20, v27, 2, s76
	ds_read_b128 v[0:3], v25 offset:17600
	ds_read_b32 v28, v20
	s_waitcnt lgkmcnt(4)
	v_mfma_f32_16x16x32_bf16 v[20:23], v[12:15], v[4:7], 0
	ds_read_b128 v[30:33], v29 offset:128
	ds_read_b128 v[12:15], v25 offset:17536
	ds_read_b128 v[34:37], v29 offset:192
	s_waitcnt lgkmcnt(5)
	v_mfma_f32_16x16x32_bf16 v[16:19], v[16:19], v[8:11], v[20:23]
	s_waitcnt lgkmcnt(1)
	v_mfma_f32_16x16x32_bf16 v[16:19], v[30:33], v[12:15], v[16:19]
	v_ashrrev_i32_e32 v32, 4, v152
	v_lshlrev_b32_e32 v20, 2, v32
	v_ashrrev_i32_e32 v21, 31, v20
	s_waitcnt lgkmcnt(0)
	v_mfma_f32_16x16x32_bf16 v[16:19], v[34:37], v[0:3], v[16:19]
	v_cmp_le_i32_e32 vcc, v20, v27
	v_lshl_add_u32 v29, v20, 2, s76
	v_mov_b32_e32 v30, 0
	s_and_saveexec_b64 s[8:9], vcc
	s_cbranch_execz .LBB0_230
	ds_read_b32 v22, v29
	s_waitcnt lgkmcnt(0)
	v_sub_f32_e32 v22, v28, v22
	v_mul_f32_e32 v22, 0x3fb8aa3b, v22
	v_exp_f32_e32 v22, v22
	s_nop 0
	v_mul_f32_e32 v30, v16, v22
